# back-edge rotation: GEMM K-loop counter/pointer SALU moved from after the loop-back barrier into the last MFMA block (5 loops)
# baseline (speedup 1.0000x reference)
; #define G_STAGE(bufoff, gbase, voff) do { _Pragma("unroll") for (int _i = 0; _i < 2; ++_i) \
;         __builtin_amdgcn_global_load_lds((const unsigned*)((const char*)(gbase) + (voff)[_i]), (LAS unsigned*)(lds + (bufoff) + ldsw + _i * 8192), 16, 0, 0); } while (0)
; #define G_LDA(dst, b, h) do { _Pragma("unroll") for (int m = 0; m < 4; ++m) _Pragma("unroll") for (int k = 0; k < 2; ++k) dst[m][k] = *(const LAS bf16x8*)(lds + G_SA(b, h) + aoff + m * 2048 + k * 1024); } while (0)
; #define G_LDB(dst, b, h) do { _Pragma("unroll") for (int n = 0; n < 2; ++n) _Pragma("unroll") for (int k = 0; k < 2; ++k) dst[n][k] = *(const LAS bf16x8*)(lds + G_SB(b, h) + boff + n * 2048 + k * 1024); } while (0)
; #define G_MMA(ai, bj, At, Bt_) do { __builtin_amdgcn_s_setprio(1); _Pragma("unroll") for (int m = 0; m < 4; ++m) _Pragma("unroll") for (int n = 0; n < 2; ++n) _Pragma("unroll") for (int k = 0; k < 2; ++k) \
;         acc[ai][bj][m][n] = __builtin_amdgcn_mfma_f32_16x16x32_bf16(Bt_[n][k], At[m][k], acc[ai][bj][m][n], 0, 0, 0); __builtin_amdgcn_s_setprio(0); } while (0)
; #define G_WAIT_V(n) asm volatile("s_waitcnt vmcnt(" #n ")" ::: "memory")
; #define G_WAIT_L(n) asm volatile("s_waitcnt lgkmcnt(" #n ")" ::: "memory")
; #define G_BAR __builtin_amdgcn_s_barrier()
; #define G_SCHED __builtin_amdgcn_sched_barrier(0)
; template <int NSTORE, class TF, class F>
; DEVI void gemm_run(const bf16_t* __restrict__ A, int lda, const bf16_t* __restrict__ Bt, int ldb, int K, bf16_t* shm, TF&& tile, F&& emit) {
;     ...
;         for (int t = 0; t < nt; t += 2) {
;             const bool last = (t == nt - 2);
;             const char* a1 = cA + (size_t)(t + 1) * kstep;
;             const char* a2 = last ? nA : cA + (size_t)(t + 2) * kstep; const char* b2 = last ? nB : cB + (size_t)(t + 2) * kstep;
;             const char* a3 = a2 + kstep; const char* b3 = b2 + kstep;
;             G_LDB(B0, 0, 0); G_LDB(B1, 0, 1); G_SCHED; G_LDA(At, 0, 0); G_STAGE(G_SA(1, 1), a1 + hstepA, voffA);
;             G_WAIT_V(8); G_WAIT_L(0); G_BAR; G_MMA(0, 0, At, B0); G_MMA(0, 1, At, B1); G_BAR; G_SCHED;
;             G_LDA(At, 0, 1); G_STAGE(G_SB(0, 0), b2, voffB); G_STAGE(G_SB(0, 1), b2 + hstepB, voffB); G_STAGE(G_SA(0, 0), a2, voffA);
;             G_WAIT_V(8); G_WAIT_L(0); G_BAR; G_MMA(1, 0, At, B0); G_MMA(1, 1, At, B1); G_BAR; G_SCHED;
.LBB0_452:
	v_or_b32_e32 v144, 0x10000, v142
	v_add_u32_e32 v148, 0x10400, v142
	v_add_u32_e32 v152, 0x10800, v142
	v_add_u32_e32 v156, 0x10c00, v142
	v_or_b32_e32 v160, 0x14000, v142
	v_add_u32_e32 v164, 0x14400, v142
	v_add_u32_e32 v168, 0x14800, v142
	v_add_u32_e32 v176, 0x14c00, v142
	ds_read_b128 v[144:147], v144
	ds_read_b128 v[148:151], v148
	ds_read_b128 v[152:155], v152
	ds_read_b128 v[156:159], v156
	ds_read_b128 v[160:163], v160
	ds_read_b128 v[164:167], v164
	ds_read_b128 v[168:171], v168
	ds_read_b128 v[176:179], v176
	s_add_u32 s28, s70, 0xfffc0080
	s_addc_u32 s29, s71, -1
	s_cmp_eq_u32 s82, 12
	s_cselect_b32 s75, s41, s29
	s_cselect_b32 s74, s94, s28
	s_cselect_b32 s73, s43, s3
	s_cselect_b32 s72, s95, s33
	v_lshl_add_u64 v[216:217], s[70:71], 0, v[136:137]
	s_add_i32 m0, s14, 0xc000
	ds_read_b128 v[182:185], v141
	ds_read_b128 v[188:191], v141 offset:1024
	ds_read_b128 v[192:195], v141 offset:2048
	ds_read_b128 v[196:199], v141 offset:3072
	ds_read_b128 v[200:203], v141 offset:4096
	ds_read_b128 v[204:207], v141 offset:5120
	ds_read_b128 v[208:211], v141 offset:6144
	ds_read_b128 v[212:215], v141 offset:7168
	global_load_lds_dwordx4 v[216:217], off
	v_lshl_add_u64 v[216:217], s[70:71], 0, v[138:139]
	s_add_i32 m0, s14, 0xe000
	s_nop 0
	global_load_lds_dwordx4 v[216:217], off
	s_waitcnt vmcnt(8)
	s_waitcnt lgkmcnt(0)
	s_barrier
	s_setprio 1
	s_waitcnt lgkmcnt(0)
	v_mfma_f32_16x16x32_bf16 v[126:129], v[144:147], v[182:185], v[126:129]
	v_mfma_f32_16x16x32_bf16 v[122:125], v[152:155], v[182:185], v[122:125]
	v_mfma_f32_16x16x32_bf16 v[118:121], v[144:147], v[192:195], v[118:121]
	v_mfma_f32_16x16x32_bf16 v[114:117], v[152:155], v[192:195], v[114:117]
	v_mfma_f32_16x16x32_bf16 v[102:105], v[144:147], v[200:203], v[102:105]
	v_mfma_f32_16x16x32_bf16 v[98:101], v[152:155], v[200:203], v[98:101]
	v_mfma_f32_16x16x32_bf16 v[86:89], v[144:147], v[208:211], v[86:89]
	v_mfma_f32_16x16x32_bf16 v[82:85], v[152:155], v[208:211], v[82:85]
	v_mfma_f32_16x16x32_bf16 v[126:129], v[148:151], v[188:191], v[126:129]
	v_mfma_f32_16x16x32_bf16 v[122:125], v[156:159], v[188:191], v[122:125]
	v_mfma_f32_16x16x32_bf16 v[118:121], v[148:151], v[196:199], v[118:121]
	v_mfma_f32_16x16x32_bf16 v[114:117], v[156:159], v[196:199], v[114:117]
	v_mfma_f32_16x16x32_bf16 v[102:105], v[148:151], v[204:207], v[102:105]
	v_mfma_f32_16x16x32_bf16 v[98:101], v[156:159], v[204:207], v[98:101]
	v_mfma_f32_16x16x32_bf16 v[86:89], v[148:151], v[212:215], v[86:89]
	v_mfma_f32_16x16x32_bf16 v[82:85], v[156:159], v[212:215], v[82:85]
	s_setprio 0
	s_setprio 1
	v_mfma_f32_16x16x32_bf16 v[110:113], v[160:163], v[182:185], v[110:113]
	v_mfma_f32_16x16x32_bf16 v[106:109], v[168:171], v[182:185], v[106:109]
	v_mfma_f32_16x16x32_bf16 v[94:97], v[160:163], v[192:195], v[94:97]
	v_mfma_f32_16x16x32_bf16 v[90:93], v[168:171], v[192:195], v[90:93]
	v_mfma_f32_16x16x32_bf16 v[78:81], v[160:163], v[200:203], v[78:81]
	v_mfma_f32_16x16x32_bf16 v[74:77], v[168:171], v[200:203], v[74:77]
	v_mfma_f32_16x16x32_bf16 v[70:73], v[160:163], v[208:211], v[70:73]
	v_mfma_f32_16x16x32_bf16 v[66:69], v[168:171], v[208:211], v[66:69]
	v_mfma_f32_16x16x32_bf16 v[110:113], v[164:167], v[188:191], v[110:113]
	v_mfma_f32_16x16x32_bf16 v[106:109], v[176:179], v[188:191], v[106:109]
	v_mfma_f32_16x16x32_bf16 v[94:97], v[164:167], v[196:199], v[94:97]
	v_mfma_f32_16x16x32_bf16 v[90:93], v[176:179], v[196:199], v[90:93]
	v_mfma_f32_16x16x32_bf16 v[78:81], v[164:167], v[204:207], v[78:81]
	v_mfma_f32_16x16x32_bf16 v[74:77], v[176:179], v[204:207], v[74:77]
	v_mfma_f32_16x16x32_bf16 v[70:73], v[164:167], v[212:215], v[70:73]
	v_mfma_f32_16x16x32_bf16 v[66:69], v[176:179], v[212:215], v[66:69]
	s_setprio 0
	s_barrier
	s_mov_b32 m0, s15
	v_lshl_add_u64 v[216:217], s[72:73], 0, v[0:1]
	s_add_u32 s28, s72, 0x40000
	ds_read_b128 v[182:185], v141 offset:16384
	ds_read_b128 v[188:191], v141 offset:17408
	ds_read_b128 v[192:195], v141 offset:18432
	ds_read_b128 v[196:199], v141 offset:19456
	ds_read_b128 v[200:203], v141 offset:20480
	ds_read_b128 v[204:207], v141 offset:21504
	ds_read_b128 v[208:211], v141 offset:22528
	ds_read_b128 v[212:215], v141 offset:23552
	global_load_lds_dwordx4 v[216:217], off
	v_lshl_add_u64 v[218:219], s[72:73], 0, v[130:131]
	s_mov_b32 m0, s16
	s_addc_u32 s29, s73, 0
	global_load_lds_dwordx4 v[218:219], off
	v_lshl_add_u64 v[220:221], s[28:29], 0, v[0:1]
	s_mov_b32 m0, s17
	v_lshl_add_u64 v[222:223], s[74:75], 0, v[132:133]
	global_load_lds_dwordx4 v[220:221], off
	v_lshl_add_u64 v[220:221], s[28:29], 0, v[130:131]
	s_mov_b32 m0, s18
	s_nop 0
	global_load_lds_dwordx4 v[220:221], off
	v_lshl_add_u64 v[220:221], s[74:75], 0, v[134:135]
	s_mov_b32 m0, s14
	s_nop 0
	global_load_lds_dwordx4 v[220:221], off
	s_mov_b32 m0, s19
	s_nop 0
	global_load_lds_dwordx4 v[222:223], off
	s_waitcnt vmcnt(8)
	s_waitcnt lgkmcnt(0)
	s_barrier
; #define G_STAGE(bufoff, gbase, voff) do { _Pragma("unroll") for (int _i = 0; _i < 2; ++_i) \
;         __builtin_amdgcn_global_load_lds((const unsigned*)((const char*)(gbase) + (voff)[_i]), (LAS unsigned*)(lds + (bufoff) + ldsw + _i * 8192), 16, 0, 0); } while (0)
; #define G_LDA(dst, b, h) do { _Pragma("unroll") for (int m = 0; m < 4; ++m) _Pragma("unroll") for (int k = 0; k < 2; ++k) dst[m][k] = *(const LAS bf16x8*)(lds + G_SA(b, h) + aoff + m * 2048 + k * 1024); } while (0)
; #define G_LDB(dst, b, h) do { _Pragma("unroll") for (int n = 0; n < 2; ++n) _Pragma("unroll") for (int k = 0; k < 2; ++k) dst[n][k] = *(const LAS bf16x8*)(lds + G_SB(b, h) + boff + n * 2048 + k * 1024); } while (0)
; #define G_MMA(ai, bj, At, Bt_) do { __builtin_amdgcn_s_setprio(1); _Pragma("unroll") for (int m = 0; m < 4; ++m) _Pragma("unroll") for (int n = 0; n < 2; ++n) _Pragma("unroll") for (int k = 0; k < 2; ++k) \
;         acc[ai][bj][m][n] = __builtin_amdgcn_mfma_f32_16x16x32_bf16(Bt_[n][k], At[m][k], acc[ai][bj][m][n], 0, 0, 0); __builtin_amdgcn_s_setprio(0); } while (0)
; #define G_WAIT_V(n) asm volatile("s_waitcnt vmcnt(" #n ")" ::: "memory")
; #define G_WAIT_L(n) asm volatile("s_waitcnt lgkmcnt(" #n ")" ::: "memory")
; #define G_BAR __builtin_amdgcn_s_barrier()
; #define G_SCHED __builtin_amdgcn_sched_barrier(0)
; template <int NSTORE, class TF, class F>
; DEVI void gemm_run(const bf16_t* __restrict__ A, int lda, const bf16_t* __restrict__ Bt, int ldb, int K, bf16_t* shm, TF&& tile, F&& emit) {
;     ...
;             G_WAIT_V(8); G_WAIT_L(0); G_BAR; G_MMA(0, 0, At, B0); G_MMA(0, 1, At, B1); G_BAR; G_SCHED;
;             G_LDA(At, 0, 1); G_STAGE(G_SB(0, 0), b2, voffB); G_STAGE(G_SB(0, 1), b2 + hstepB, voffB); G_STAGE(G_SA(0, 0), a2, voffA);
;             G_WAIT_V(8); G_WAIT_L(0); G_BAR; G_MMA(1, 0, At, B0); G_MMA(1, 1, At, B1); G_BAR; G_SCHED;
;             G_LDB(B0, 1, 0); G_LDB(B1, 1, 1); G_SCHED; G_LDA(At, 1, 0); G_STAGE(G_SA(0, 1), a2 + hstepA, voffA);
;             G_WAIT_V(8); G_WAIT_L(0); G_BAR; G_MMA(0, 0, At, B0); G_MMA(0, 1, At, B1); G_BAR; G_SCHED;
	s_setprio 1
	s_waitcnt lgkmcnt(0)
	v_mfma_f32_16x16x32_bf16 v[62:65], v[144:147], v[182:185], v[62:65]
	v_mfma_f32_16x16x32_bf16 v[58:61], v[152:155], v[182:185], v[58:61]
	v_mfma_f32_16x16x32_bf16 v[54:57], v[144:147], v[192:195], v[54:57]
	v_mfma_f32_16x16x32_bf16 v[50:53], v[152:155], v[192:195], v[50:53]
	v_mfma_f32_16x16x32_bf16 v[38:41], v[144:147], v[200:203], v[38:41]
	v_mfma_f32_16x16x32_bf16 v[34:37], v[152:155], v[200:203], v[34:37]
	v_mfma_f32_16x16x32_bf16 v[22:25], v[144:147], v[208:211], v[22:25]
	v_mfma_f32_16x16x32_bf16 v[18:21], v[152:155], v[208:211], v[18:21]
	v_mfma_f32_16x16x32_bf16 v[62:65], v[148:151], v[188:191], v[62:65]
	v_mfma_f32_16x16x32_bf16 v[58:61], v[156:159], v[188:191], v[58:61]
	v_mfma_f32_16x16x32_bf16 v[54:57], v[148:151], v[196:199], v[54:57]
	v_mfma_f32_16x16x32_bf16 v[50:53], v[156:159], v[196:199], v[50:53]
	v_mfma_f32_16x16x32_bf16 v[38:41], v[148:151], v[204:207], v[38:41]
	v_mfma_f32_16x16x32_bf16 v[34:37], v[156:159], v[204:207], v[34:37]
	v_mfma_f32_16x16x32_bf16 v[22:25], v[148:151], v[212:215], v[22:25]
	v_mfma_f32_16x16x32_bf16 v[18:21], v[156:159], v[212:215], v[18:21]
	s_setprio 0
	s_setprio 1
	v_mfma_f32_16x16x32_bf16 v[46:49], v[160:163], v[182:185], v[46:49]
	v_mfma_f32_16x16x32_bf16 v[42:45], v[168:171], v[182:185], v[42:45]
	v_mfma_f32_16x16x32_bf16 v[30:33], v[160:163], v[192:195], v[30:33]
	v_mfma_f32_16x16x32_bf16 v[26:29], v[168:171], v[192:195], v[26:29]
	v_mfma_f32_16x16x32_bf16 v[14:17], v[160:163], v[200:203], v[14:17]
	v_mfma_f32_16x16x32_bf16 v[10:13], v[168:171], v[200:203], v[10:13]
	v_mfma_f32_16x16x32_bf16 v[6:9], v[160:163], v[208:211], v[6:9]
	v_mfma_f32_16x16x32_bf16 v[2:5], v[168:171], v[208:211], v[2:5]
	v_mfma_f32_16x16x32_bf16 v[46:49], v[164:167], v[188:191], v[46:49]
	v_mfma_f32_16x16x32_bf16 v[42:45], v[176:179], v[188:191], v[42:45]
	v_mfma_f32_16x16x32_bf16 v[30:33], v[164:167], v[196:199], v[30:33]
	v_mfma_f32_16x16x32_bf16 v[26:29], v[176:179], v[196:199], v[26:29]
	v_mfma_f32_16x16x32_bf16 v[14:17], v[164:167], v[204:207], v[14:17]
	v_mfma_f32_16x16x32_bf16 v[10:13], v[176:179], v[204:207], v[10:13]
	v_mfma_f32_16x16x32_bf16 v[6:9], v[164:167], v[212:215], v[6:9]
	v_mfma_f32_16x16x32_bf16 v[2:5], v[176:179], v[212:215], v[2:5]
	s_setprio 0
	s_barrier
	v_or_b32_e32 v144, 0x18000, v142
	v_add_u32_e32 v148, 0x18400, v142
	v_add_u32_e32 v152, 0x18800, v142
	v_add_u32_e32 v156, 0x18c00, v142
	v_or_b32_e32 v160, 0x1c000, v142
	v_add_u32_e32 v164, 0x1c400, v142
	v_add_u32_e32 v168, 0x1c800, v142
	v_add_u32_e32 v176, 0x1cc00, v142
	ds_read_b128 v[144:147], v144
	ds_read_b128 v[148:151], v148
	ds_read_b128 v[152:155], v152
	ds_read_b128 v[156:159], v156
	ds_read_b128 v[160:163], v160
	ds_read_b128 v[164:167], v164
	ds_read_b128 v[168:171], v168
	ds_read_b128 v[176:179], v176
	s_add_u32 s28, s74, 0x40000
	s_addc_u32 s29, s75, 0
	s_mov_b32 m0, s76
	v_lshl_add_u64 v[224:225], s[28:29], 0, v[134:135]
	ds_read_b128 v[182:185], v141 offset:32768
	ds_read_b128 v[188:191], v141 offset:33792
	ds_read_b128 v[192:195], v141 offset:34816
	ds_read_b128 v[196:199], v141 offset:35840
	ds_read_b128 v[200:203], v141 offset:36864
	ds_read_b128 v[204:207], v141 offset:37888
	ds_read_b128 v[208:211], v141 offset:38912
	ds_read_b128 v[212:215], v141 offset:39936
	global_load_lds_dwordx4 v[224:225], off
	v_lshl_add_u64 v[224:225], s[28:29], 0, v[132:133]
	s_mov_b32 m0, s77
	s_nop 0
	global_load_lds_dwordx4 v[224:225], off
	s_waitcnt vmcnt(8)
	s_waitcnt lgkmcnt(0)
	s_barrier
	s_setprio 1
	s_waitcnt lgkmcnt(0)
	v_mfma_f32_16x16x32_bf16 v[126:129], v[144:147], v[182:185], v[126:129]
	v_mfma_f32_16x16x32_bf16 v[122:125], v[152:155], v[182:185], v[122:125]
	v_mfma_f32_16x16x32_bf16 v[118:121], v[144:147], v[192:195], v[118:121]
	v_mfma_f32_16x16x32_bf16 v[114:117], v[152:155], v[192:195], v[114:117]
	v_mfma_f32_16x16x32_bf16 v[102:105], v[144:147], v[200:203], v[102:105]
	v_mfma_f32_16x16x32_bf16 v[98:101], v[152:155], v[200:203], v[98:101]
	v_mfma_f32_16x16x32_bf16 v[86:89], v[144:147], v[208:211], v[86:89]
	v_mfma_f32_16x16x32_bf16 v[82:85], v[152:155], v[208:211], v[82:85]
	v_mfma_f32_16x16x32_bf16 v[126:129], v[148:151], v[188:191], v[126:129]
	v_mfma_f32_16x16x32_bf16 v[122:125], v[156:159], v[188:191], v[122:125]
	v_mfma_f32_16x16x32_bf16 v[118:121], v[148:151], v[196:199], v[118:121]
	v_mfma_f32_16x16x32_bf16 v[114:117], v[156:159], v[196:199], v[114:117]
	v_mfma_f32_16x16x32_bf16 v[102:105], v[148:151], v[204:207], v[102:105]
	v_mfma_f32_16x16x32_bf16 v[98:101], v[156:159], v[204:207], v[98:101]
	v_mfma_f32_16x16x32_bf16 v[86:89], v[148:151], v[212:215], v[86:89]
	v_mfma_f32_16x16x32_bf16 v[82:85], v[156:159], v[212:215], v[82:85]
	s_setprio 0
	s_setprio 1
	v_mfma_f32_16x16x32_bf16 v[110:113], v[160:163], v[182:185], v[110:113]
	v_mfma_f32_16x16x32_bf16 v[106:109], v[168:171], v[182:185], v[106:109]
	v_mfma_f32_16x16x32_bf16 v[94:97], v[160:163], v[192:195], v[94:97]
	v_mfma_f32_16x16x32_bf16 v[90:93], v[168:171], v[192:195], v[90:93]
	v_mfma_f32_16x16x32_bf16 v[78:81], v[160:163], v[200:203], v[78:81]
	v_mfma_f32_16x16x32_bf16 v[74:77], v[168:171], v[200:203], v[74:77]
	v_mfma_f32_16x16x32_bf16 v[70:73], v[160:163], v[208:211], v[70:73]
	v_mfma_f32_16x16x32_bf16 v[66:69], v[168:171], v[208:211], v[66:69]
	v_mfma_f32_16x16x32_bf16 v[110:113], v[164:167], v[188:191], v[110:113]
	v_mfma_f32_16x16x32_bf16 v[106:109], v[176:179], v[188:191], v[106:109]
	v_mfma_f32_16x16x32_bf16 v[94:97], v[164:167], v[196:199], v[94:97]
	v_mfma_f32_16x16x32_bf16 v[90:93], v[176:179], v[196:199], v[90:93]
	v_mfma_f32_16x16x32_bf16 v[78:81], v[164:167], v[204:207], v[78:81]
	v_mfma_f32_16x16x32_bf16 v[74:77], v[176:179], v[204:207], v[74:77]
	v_mfma_f32_16x16x32_bf16 v[70:73], v[164:167], v[212:215], v[70:73]
	v_mfma_f32_16x16x32_bf16 v[66:69], v[176:179], v[212:215], v[66:69]
	s_setprio 0
	s_barrier
; #define G_STAGE(bufoff, gbase, voff) do { _Pragma("unroll") for (int _i = 0; _i < 2; ++_i) \
;         __builtin_amdgcn_global_load_lds((const unsigned*)((const char*)(gbase) + (voff)[_i]), (LAS unsigned*)(lds + (bufoff) + ldsw + _i * 8192), 16, 0, 0); } while (0)
; #define G_LDA(dst, b, h) do { _Pragma("unroll") for (int m = 0; m < 4; ++m) _Pragma("unroll") for (int k = 0; k < 2; ++k) dst[m][k] = *(const LAS bf16x8*)(lds + G_SA(b, h) + aoff + m * 2048 + k * 1024); } while (0)
; #define G_MMA(ai, bj, At, Bt_) do { __builtin_amdgcn_s_setprio(1); _Pragma("unroll") for (int m = 0; m < 4; ++m) _Pragma("unroll") for (int n = 0; n < 2; ++n) _Pragma("unroll") for (int k = 0; k < 2; ++k) \
;         acc[ai][bj][m][n] = __builtin_amdgcn_mfma_f32_16x16x32_bf16(Bt_[n][k], At[m][k], acc[ai][bj][m][n], 0, 0, 0); __builtin_amdgcn_s_setprio(0); } while (0)
; #define G_WAIT_V(n) asm volatile("s_waitcnt vmcnt(" #n ")" ::: "memory")
; #define G_WAIT_L(n) asm volatile("s_waitcnt lgkmcnt(" #n ")" ::: "memory")
; #define G_BAR __builtin_amdgcn_s_barrier()
; #define G_SCHED __builtin_amdgcn_sched_barrier(0)
; template <int NSTORE, class TF, class F>
; DEVI void gemm_run(const bf16_t* __restrict__ A, int lda, const bf16_t* __restrict__ Bt, int ldb, int K, bf16_t* shm, TF&& tile, F&& emit) {
;     ...
;             G_LDA(At, 1, 1); G_STAGE(G_SB(1, 0), b3, voffB); G_STAGE(G_SB(1, 1), b3 + hstepB, voffB); G_STAGE(G_SA(1, 0), a3, voffA);
;             G_WAIT_V(8); G_WAIT_L(0); G_BAR; G_MMA(1, 0, At, B0); G_MMA(1, 1, At, B1); G_BAR; G_SCHED;
;         }
	s_mov_b32 m0, s8
	v_lshl_add_u64 v[216:217], v[216:217], 0, s[30:31]
	s_add_u32 s28, s72, 0x40080
	ds_read_b128 v[182:185], v141 offset:49152
	ds_read_b128 v[188:191], v141 offset:50176
	ds_read_b128 v[192:195], v141 offset:51200
	ds_read_b128 v[196:199], v141 offset:52224
	ds_read_b128 v[200:203], v141 offset:53248
	ds_read_b128 v[204:207], v141 offset:54272
	ds_read_b128 v[208:211], v141 offset:55296
	ds_read_b128 v[212:215], v141 offset:56320
	global_load_lds_dwordx4 v[216:217], off
	v_lshl_add_u64 v[216:217], v[218:219], 0, s[30:31]
	s_mov_b32 m0, s9
	s_addc_u32 s29, s73, 0
	global_load_lds_dwordx4 v[216:217], off
	v_lshl_add_u64 v[216:217], s[28:29], 0, v[0:1]
	s_mov_b32 m0, s78
	s_nop 0
	global_load_lds_dwordx4 v[216:217], off
	v_lshl_add_u64 v[216:217], s[28:29], 0, v[130:131]
	s_mov_b32 m0, s79
	s_nop 0
	global_load_lds_dwordx4 v[216:217], off
	v_lshl_add_u64 v[216:217], v[220:221], 0, s[30:31]
	s_mov_b32 m0, s26
	s_nop 0
	global_load_lds_dwordx4 v[216:217], off
	v_lshl_add_u64 v[216:217], v[222:223], 0, s[30:31]
	s_mov_b32 m0, s27
	s_nop 0
	global_load_lds_dwordx4 v[216:217], off
	s_waitcnt vmcnt(8)
	s_waitcnt lgkmcnt(0)
	s_barrier
	s_setprio 1
	s_waitcnt lgkmcnt(0)
	v_mfma_f32_16x16x32_bf16 v[62:65], v[144:147], v[182:185], v[62:65]
	v_mfma_f32_16x16x32_bf16 v[58:61], v[152:155], v[182:185], v[58:61]
	v_mfma_f32_16x16x32_bf16 v[54:57], v[144:147], v[192:195], v[54:57]
	v_mfma_f32_16x16x32_bf16 v[50:53], v[152:155], v[192:195], v[50:53]
	v_mfma_f32_16x16x32_bf16 v[38:41], v[144:147], v[200:203], v[38:41]
	v_mfma_f32_16x16x32_bf16 v[34:37], v[152:155], v[200:203], v[34:37]
	v_mfma_f32_16x16x32_bf16 v[22:25], v[144:147], v[208:211], v[22:25]
	v_mfma_f32_16x16x32_bf16 v[18:21], v[152:155], v[208:211], v[18:21]
	v_mfma_f32_16x16x32_bf16 v[62:65], v[148:151], v[188:191], v[62:65]
	v_mfma_f32_16x16x32_bf16 v[58:61], v[156:159], v[188:191], v[58:61]
	v_mfma_f32_16x16x32_bf16 v[54:57], v[148:151], v[196:199], v[54:57]
	v_mfma_f32_16x16x32_bf16 v[50:53], v[156:159], v[196:199], v[50:53]
	v_mfma_f32_16x16x32_bf16 v[38:41], v[148:151], v[204:207], v[38:41]
	v_mfma_f32_16x16x32_bf16 v[34:37], v[156:159], v[204:207], v[34:37]
	v_mfma_f32_16x16x32_bf16 v[22:25], v[148:151], v[212:215], v[22:25]
	v_mfma_f32_16x16x32_bf16 v[18:21], v[156:159], v[212:215], v[18:21]
	s_setprio 0
	s_setprio 1
	v_mfma_f32_16x16x32_bf16 v[46:49], v[160:163], v[182:185], v[46:49]
	v_mfma_f32_16x16x32_bf16 v[42:45], v[168:171], v[182:185], v[42:45]
	v_mfma_f32_16x16x32_bf16 v[30:33], v[160:163], v[192:195], v[30:33]
	v_mfma_f32_16x16x32_bf16 v[26:29], v[168:171], v[192:195], v[26:29]
	v_mfma_f32_16x16x32_bf16 v[14:17], v[160:163], v[200:203], v[14:17]
	s_add_i32 s82, s82, 2
	v_mfma_f32_16x16x32_bf16 v[10:13], v[168:171], v[200:203], v[10:13]
	v_mfma_f32_16x16x32_bf16 v[6:9], v[160:163], v[208:211], v[6:9]
	s_add_u32 s70, s70, 0x100
	v_mfma_f32_16x16x32_bf16 v[2:5], v[168:171], v[208:211], v[2:5]
	v_mfma_f32_16x16x32_bf16 v[46:49], v[164:167], v[188:191], v[46:49]
	s_addc_u32 s71, s71, 0
	v_mfma_f32_16x16x32_bf16 v[42:45], v[176:179], v[188:191], v[42:45]
	v_mfma_f32_16x16x32_bf16 v[30:33], v[164:167], v[196:199], v[30:33]
	s_add_u32 s33, s33, 0x100
	v_mfma_f32_16x16x32_bf16 v[26:29], v[176:179], v[196:199], v[26:29]
	v_mfma_f32_16x16x32_bf16 v[14:17], v[164:167], v[204:207], v[14:17]
	s_addc_u32 s3, s3, 0
	v_mfma_f32_16x16x32_bf16 v[10:13], v[176:179], v[204:207], v[10:13]
	v_mfma_f32_16x16x32_bf16 v[6:9], v[164:167], v[212:215], v[6:9]
	s_cmp_gt_u32 s82, 13
	v_mfma_f32_16x16x32_bf16 v[2:5], v[176:179], v[212:215], v[2:5]
	s_setprio 0
	s_barrier
	s_cbranch_scc0 .LBB0_452
	s_and_b64 vcc, exec, s[38:39]
	s_cbranch_vccz .LBB0_455
	s_barrier

; #define G_STAGE(bufoff, gbase, voff) do { _Pragma("unroll") for (int _i = 0; _i < 2; ++_i) \
;         __builtin_amdgcn_global_load_lds((const unsigned*)((const char*)(gbase) + (voff)[_i]), (LAS unsigned*)(lds + (bufoff) + ldsw + _i * 8192), 16, 0, 0); } while (0)
; #define G_LDA(dst, b, h) do { _Pragma("unroll") for (int m = 0; m < 4; ++m) _Pragma("unroll") for (int k = 0; k < 2; ++k) dst[m][k] = *(const LAS bf16x8*)(lds + G_SA(b, h) + aoff + m * 2048 + k * 1024); } while (0)
; #define G_LDB(dst, b, h) do { _Pragma("unroll") for (int n = 0; n < 2; ++n) _Pragma("unroll") for (int k = 0; k < 2; ++k) dst[n][k] = *(const LAS bf16x8*)(lds + G_SB(b, h) + boff + n * 2048 + k * 1024); } while (0)
; #define G_MMA(ai, bj, At, Bt_) do { __builtin_amdgcn_s_setprio(1); _Pragma("unroll") for (int m = 0; m < 4; ++m) _Pragma("unroll") for (int n = 0; n < 2; ++n) _Pragma("unroll") for (int k = 0; k < 2; ++k) \
;         acc[ai][bj][m][n] = __builtin_amdgcn_mfma_f32_16x16x32_bf16(Bt_[n][k], At[m][k], acc[ai][bj][m][n], 0, 0, 0); __builtin_amdgcn_s_setprio(0); } while (0)
; #define G_WAIT_V(n) asm volatile("s_waitcnt vmcnt(" #n ")" ::: "memory")
; #define G_WAIT_L(n) asm volatile("s_waitcnt lgkmcnt(" #n ")" ::: "memory")
; #define G_BAR __builtin_amdgcn_s_barrier()
; #define G_SCHED __builtin_amdgcn_sched_barrier(0)
; template <int NSTORE, class TF, class F>
; DEVI void gemm_run(const bf16_t* __restrict__ A, int lda, const bf16_t* __restrict__ Bt, int ldb, int K, bf16_t* shm, TF&& tile, F&& emit) {
;     ...
;         for (int t = 0; t < nt; t += 2) {
;             const bool last = (t == nt - 2);
;             const char* a1 = cA + (size_t)(t + 1) * kstep;
;             const char* a2 = last ? nA : cA + (size_t)(t + 2) * kstep; const char* b2 = last ? nB : cB + (size_t)(t + 2) * kstep;
;             const char* a3 = a2 + kstep; const char* b3 = b2 + kstep;
;             G_LDB(B0, 0, 0); G_LDB(B1, 0, 1); G_SCHED; G_LDA(At, 0, 0); G_STAGE(G_SA(1, 1), a1 + hstepA, voffA);
;             G_WAIT_V(8); G_WAIT_L(0); G_BAR; G_MMA(0, 0, At, B0); G_MMA(0, 1, At, B1); G_BAR; G_SCHED;
;             G_LDA(At, 0, 1); G_STAGE(G_SB(0, 0), b2, voffB); G_STAGE(G_SB(0, 1), b2 + hstepB, voffB); G_STAGE(G_SA(0, 0), a2, voffA);
;             G_WAIT_V(8); G_WAIT_L(0); G_BAR; G_MMA(1, 0, At, B0); G_MMA(1, 1, At, B1); G_BAR; G_SCHED;
.LBB0_488:
	v_or_b32_e32 v144, 0x10000, v141
	v_add_u32_e32 v148, 0x10400, v141
	v_add_u32_e32 v152, 0x10800, v141
	v_add_u32_e32 v156, 0x10c00, v141
	v_or_b32_e32 v160, 0x14000, v141
	v_add_u32_e32 v164, 0x14400, v141
	v_add_u32_e32 v168, 0x14800, v141
	v_add_u32_e32 v176, 0x14c00, v141
	ds_read_b128 v[144:147], v144
	ds_read_b128 v[148:151], v148
	ds_read_b128 v[152:155], v152
	ds_read_b128 v[156:159], v156
	ds_read_b128 v[160:163], v160
	ds_read_b128 v[164:167], v164
	ds_read_b128 v[168:171], v168
	ds_read_b128 v[176:179], v176
	s_add_u32 s28, s74, 0xfff00080
	s_addc_u32 s29, s75, -1
	s_cmp_eq_u32 s82, 60
	s_cselect_b32 s79, s43, s29
	s_cselect_b32 s78, s47, s28
	s_cselect_b32 s77, s49, s3
	s_cselect_b32 s76, s69, s33
	v_lshl_add_u64 v[216:217], s[74:75], 0, v[136:137]
	s_add_i32 m0, s14, 0xc000
	ds_read_b128 v[182:185], v142
	ds_read_b128 v[188:191], v142 offset:1024
	ds_read_b128 v[192:195], v142 offset:2048
	ds_read_b128 v[196:199], v142 offset:3072
	ds_read_b128 v[200:203], v142 offset:4096
	ds_read_b128 v[204:207], v142 offset:5120
	ds_read_b128 v[208:211], v142 offset:6144
	ds_read_b128 v[212:215], v142 offset:7168
	global_load_lds_dwordx4 v[216:217], off
	v_lshl_add_u64 v[216:217], s[74:75], 0, v[138:139]
	s_add_i32 m0, s14, 0xe000
	s_nop 0
	global_load_lds_dwordx4 v[216:217], off
	s_waitcnt vmcnt(8)
	s_waitcnt lgkmcnt(0)
	s_barrier
	s_setprio 1
	s_waitcnt lgkmcnt(0)
	v_mfma_f32_16x16x32_bf16 v[126:129], v[144:147], v[182:185], v[126:129]
	v_mfma_f32_16x16x32_bf16 v[122:125], v[152:155], v[182:185], v[122:125]
	v_mfma_f32_16x16x32_bf16 v[118:121], v[144:147], v[192:195], v[118:121]
	v_mfma_f32_16x16x32_bf16 v[114:117], v[152:155], v[192:195], v[114:117]
	v_mfma_f32_16x16x32_bf16 v[102:105], v[144:147], v[200:203], v[102:105]
	v_mfma_f32_16x16x32_bf16 v[98:101], v[152:155], v[200:203], v[98:101]
	v_mfma_f32_16x16x32_bf16 v[86:89], v[144:147], v[208:211], v[86:89]
	v_mfma_f32_16x16x32_bf16 v[82:85], v[152:155], v[208:211], v[82:85]
	v_mfma_f32_16x16x32_bf16 v[126:129], v[148:151], v[188:191], v[126:129]
	v_mfma_f32_16x16x32_bf16 v[122:125], v[156:159], v[188:191], v[122:125]
	v_mfma_f32_16x16x32_bf16 v[118:121], v[148:151], v[196:199], v[118:121]
	v_mfma_f32_16x16x32_bf16 v[114:117], v[156:159], v[196:199], v[114:117]
	v_mfma_f32_16x16x32_bf16 v[102:105], v[148:151], v[204:207], v[102:105]
	v_mfma_f32_16x16x32_bf16 v[98:101], v[156:159], v[204:207], v[98:101]
	v_mfma_f32_16x16x32_bf16 v[86:89], v[148:151], v[212:215], v[86:89]
	v_mfma_f32_16x16x32_bf16 v[82:85], v[156:159], v[212:215], v[82:85]
	s_setprio 0
	s_setprio 1
	v_mfma_f32_16x16x32_bf16 v[110:113], v[160:163], v[182:185], v[110:113]
	v_mfma_f32_16x16x32_bf16 v[106:109], v[168:171], v[182:185], v[106:109]
	v_mfma_f32_16x16x32_bf16 v[94:97], v[160:163], v[192:195], v[94:97]
	v_mfma_f32_16x16x32_bf16 v[90:93], v[168:171], v[192:195], v[90:93]
	v_mfma_f32_16x16x32_bf16 v[78:81], v[160:163], v[200:203], v[78:81]
	v_mfma_f32_16x16x32_bf16 v[74:77], v[168:171], v[200:203], v[74:77]
	v_mfma_f32_16x16x32_bf16 v[70:73], v[160:163], v[208:211], v[70:73]
	v_mfma_f32_16x16x32_bf16 v[66:69], v[168:171], v[208:211], v[66:69]
	v_mfma_f32_16x16x32_bf16 v[110:113], v[164:167], v[188:191], v[110:113]
	v_mfma_f32_16x16x32_bf16 v[106:109], v[176:179], v[188:191], v[106:109]
	v_mfma_f32_16x16x32_bf16 v[94:97], v[164:167], v[196:199], v[94:97]
	v_mfma_f32_16x16x32_bf16 v[90:93], v[176:179], v[196:199], v[90:93]
	v_mfma_f32_16x16x32_bf16 v[78:81], v[164:167], v[204:207], v[78:81]
	v_mfma_f32_16x16x32_bf16 v[74:77], v[176:179], v[204:207], v[74:77]
	v_mfma_f32_16x16x32_bf16 v[70:73], v[164:167], v[212:215], v[70:73]
	v_mfma_f32_16x16x32_bf16 v[66:69], v[176:179], v[212:215], v[66:69]
	s_setprio 0
	s_barrier
	s_mov_b32 m0, s15
	v_lshl_add_u64 v[216:217], s[76:77], 0, v[0:1]
	s_add_u32 s28, s76, 0x100000
	ds_read_b128 v[182:185], v142 offset:16384
	ds_read_b128 v[188:191], v142 offset:17408
	ds_read_b128 v[192:195], v142 offset:18432
	ds_read_b128 v[196:199], v142 offset:19456
	ds_read_b128 v[200:203], v142 offset:20480
	ds_read_b128 v[204:207], v142 offset:21504
	ds_read_b128 v[208:211], v142 offset:22528
	ds_read_b128 v[212:215], v142 offset:23552
	global_load_lds_dwordx4 v[216:217], off
	v_lshl_add_u64 v[218:219], s[76:77], 0, v[134:135]
	s_mov_b32 m0, s16
	s_addc_u32 s29, s77, 0
	global_load_lds_dwordx4 v[218:219], off
	v_lshl_add_u64 v[220:221], s[28:29], 0, v[0:1]
	s_mov_b32 m0, s17
	v_lshl_add_u64 v[222:223], s[78:79], 0, v[132:133]
	global_load_lds_dwordx4 v[220:221], off
	v_lshl_add_u64 v[220:221], s[28:29], 0, v[134:135]
	s_mov_b32 m0, s18
	s_nop 0
	global_load_lds_dwordx4 v[220:221], off
	v_lshl_add_u64 v[220:221], s[78:79], 0, v[130:131]
	s_mov_b32 m0, s14
	s_nop 0
	global_load_lds_dwordx4 v[220:221], off
	s_mov_b32 m0, s19
	s_nop 0
	global_load_lds_dwordx4 v[222:223], off
	s_waitcnt vmcnt(8)
	s_waitcnt lgkmcnt(0)
	s_barrier
; #define G_STAGE(bufoff, gbase, voff) do { _Pragma("unroll") for (int _i = 0; _i < 2; ++_i) \
;         __builtin_amdgcn_global_load_lds((const unsigned*)((const char*)(gbase) + (voff)[_i]), (LAS unsigned*)(lds + (bufoff) + ldsw + _i * 8192), 16, 0, 0); } while (0)
; #define G_LDA(dst, b, h) do { _Pragma("unroll") for (int m = 0; m < 4; ++m) _Pragma("unroll") for (int k = 0; k < 2; ++k) dst[m][k] = *(const LAS bf16x8*)(lds + G_SA(b, h) + aoff + m * 2048 + k * 1024); } while (0)
; #define G_LDB(dst, b, h) do { _Pragma("unroll") for (int n = 0; n < 2; ++n) _Pragma("unroll") for (int k = 0; k < 2; ++k) dst[n][k] = *(const LAS bf16x8*)(lds + G_SB(b, h) + boff + n * 2048 + k * 1024); } while (0)
; #define G_MMA(ai, bj, At, Bt_) do { __builtin_amdgcn_s_setprio(1); _Pragma("unroll") for (int m = 0; m < 4; ++m) _Pragma("unroll") for (int n = 0; n < 2; ++n) _Pragma("unroll") for (int k = 0; k < 2; ++k) \
;         acc[ai][bj][m][n] = __builtin_amdgcn_mfma_f32_16x16x32_bf16(Bt_[n][k], At[m][k], acc[ai][bj][m][n], 0, 0, 0); __builtin_amdgcn_s_setprio(0); } while (0)
; #define G_WAIT_V(n) asm volatile("s_waitcnt vmcnt(" #n ")" ::: "memory")
; #define G_WAIT_L(n) asm volatile("s_waitcnt lgkmcnt(" #n ")" ::: "memory")
; #define G_BAR __builtin_amdgcn_s_barrier()
; #define G_SCHED __builtin_amdgcn_sched_barrier(0)
; template <int NSTORE, class TF, class F>
; DEVI void gemm_run(const bf16_t* __restrict__ A, int lda, const bf16_t* __restrict__ Bt, int ldb, int K, bf16_t* shm, TF&& tile, F&& emit) {
;     ...
;             G_WAIT_V(8); G_WAIT_L(0); G_BAR; G_MMA(0, 0, At, B0); G_MMA(0, 1, At, B1); G_BAR; G_SCHED;
;             G_LDA(At, 0, 1); G_STAGE(G_SB(0, 0), b2, voffB); G_STAGE(G_SB(0, 1), b2 + hstepB, voffB); G_STAGE(G_SA(0, 0), a2, voffA);
;             G_WAIT_V(8); G_WAIT_L(0); G_BAR; G_MMA(1, 0, At, B0); G_MMA(1, 1, At, B1); G_BAR; G_SCHED;
;             G_LDB(B0, 1, 0); G_LDB(B1, 1, 1); G_SCHED; G_LDA(At, 1, 0); G_STAGE(G_SA(0, 1), a2 + hstepA, voffA);
;             G_WAIT_V(8); G_WAIT_L(0); G_BAR; G_MMA(0, 0, At, B0); G_MMA(0, 1, At, B1); G_BAR; G_SCHED;
	s_setprio 1
	s_waitcnt lgkmcnt(0)
	v_mfma_f32_16x16x32_bf16 v[62:65], v[144:147], v[182:185], v[62:65]
	v_mfma_f32_16x16x32_bf16 v[58:61], v[152:155], v[182:185], v[58:61]
	v_mfma_f32_16x16x32_bf16 v[54:57], v[144:147], v[192:195], v[54:57]
	v_mfma_f32_16x16x32_bf16 v[50:53], v[152:155], v[192:195], v[50:53]
	v_mfma_f32_16x16x32_bf16 v[38:41], v[144:147], v[200:203], v[38:41]
	v_mfma_f32_16x16x32_bf16 v[34:37], v[152:155], v[200:203], v[34:37]
	v_mfma_f32_16x16x32_bf16 v[22:25], v[144:147], v[208:211], v[22:25]
	v_mfma_f32_16x16x32_bf16 v[18:21], v[152:155], v[208:211], v[18:21]
	v_mfma_f32_16x16x32_bf16 v[62:65], v[148:151], v[188:191], v[62:65]
	v_mfma_f32_16x16x32_bf16 v[58:61], v[156:159], v[188:191], v[58:61]
	v_mfma_f32_16x16x32_bf16 v[54:57], v[148:151], v[196:199], v[54:57]
	v_mfma_f32_16x16x32_bf16 v[50:53], v[156:159], v[196:199], v[50:53]
	v_mfma_f32_16x16x32_bf16 v[38:41], v[148:151], v[204:207], v[38:41]
	v_mfma_f32_16x16x32_bf16 v[34:37], v[156:159], v[204:207], v[34:37]
	v_mfma_f32_16x16x32_bf16 v[22:25], v[148:151], v[212:215], v[22:25]
	v_mfma_f32_16x16x32_bf16 v[18:21], v[156:159], v[212:215], v[18:21]
	s_setprio 0
	s_setprio 1
	v_mfma_f32_16x16x32_bf16 v[46:49], v[160:163], v[182:185], v[46:49]
	v_mfma_f32_16x16x32_bf16 v[42:45], v[168:171], v[182:185], v[42:45]
	v_mfma_f32_16x16x32_bf16 v[30:33], v[160:163], v[192:195], v[30:33]
	v_mfma_f32_16x16x32_bf16 v[26:29], v[168:171], v[192:195], v[26:29]
	v_mfma_f32_16x16x32_bf16 v[14:17], v[160:163], v[200:203], v[14:17]
	v_mfma_f32_16x16x32_bf16 v[10:13], v[168:171], v[200:203], v[10:13]
	v_mfma_f32_16x16x32_bf16 v[6:9], v[160:163], v[208:211], v[6:9]
	v_mfma_f32_16x16x32_bf16 v[2:5], v[168:171], v[208:211], v[2:5]
	v_mfma_f32_16x16x32_bf16 v[46:49], v[164:167], v[188:191], v[46:49]
	v_mfma_f32_16x16x32_bf16 v[42:45], v[176:179], v[188:191], v[42:45]
	v_mfma_f32_16x16x32_bf16 v[30:33], v[164:167], v[196:199], v[30:33]
	v_mfma_f32_16x16x32_bf16 v[26:29], v[176:179], v[196:199], v[26:29]
	v_mfma_f32_16x16x32_bf16 v[14:17], v[164:167], v[204:207], v[14:17]
	v_mfma_f32_16x16x32_bf16 v[10:13], v[176:179], v[204:207], v[10:13]
	v_mfma_f32_16x16x32_bf16 v[6:9], v[164:167], v[212:215], v[6:9]
	v_mfma_f32_16x16x32_bf16 v[2:5], v[176:179], v[212:215], v[2:5]
	s_setprio 0
	s_barrier
	v_or_b32_e32 v144, 0x18000, v141
	v_add_u32_e32 v148, 0x18400, v141
	v_add_u32_e32 v152, 0x18800, v141
	v_add_u32_e32 v156, 0x18c00, v141
	v_or_b32_e32 v160, 0x1c000, v141
	v_add_u32_e32 v164, 0x1c400, v141
	v_add_u32_e32 v168, 0x1c800, v141
	v_add_u32_e32 v176, 0x1cc00, v141
	ds_read_b128 v[144:147], v144
	ds_read_b128 v[148:151], v148
	ds_read_b128 v[152:155], v152
	ds_read_b128 v[156:159], v156
	ds_read_b128 v[160:163], v160
	ds_read_b128 v[164:167], v164
	ds_read_b128 v[168:171], v168
	ds_read_b128 v[176:179], v176
	s_add_u32 s28, s78, 0x100000
	s_addc_u32 s29, s79, 0
	s_mov_b32 m0, s45
	v_lshl_add_u64 v[224:225], s[28:29], 0, v[130:131]
	ds_read_b128 v[182:185], v142 offset:32768
	ds_read_b128 v[188:191], v142 offset:33792
	ds_read_b128 v[192:195], v142 offset:34816
	ds_read_b128 v[196:199], v142 offset:35840
	ds_read_b128 v[200:203], v142 offset:36864
	ds_read_b128 v[204:207], v142 offset:37888
	ds_read_b128 v[208:211], v142 offset:38912
	ds_read_b128 v[212:215], v142 offset:39936
	global_load_lds_dwordx4 v[224:225], off
	v_lshl_add_u64 v[224:225], s[28:29], 0, v[132:133]
	s_mov_b32 m0, s83
	s_nop 0
	global_load_lds_dwordx4 v[224:225], off
	s_waitcnt vmcnt(8)
	s_waitcnt lgkmcnt(0)
	s_barrier
	s_setprio 1
	s_waitcnt lgkmcnt(0)
	v_mfma_f32_16x16x32_bf16 v[126:129], v[144:147], v[182:185], v[126:129]
	v_mfma_f32_16x16x32_bf16 v[122:125], v[152:155], v[182:185], v[122:125]
	v_mfma_f32_16x16x32_bf16 v[118:121], v[144:147], v[192:195], v[118:121]
	v_mfma_f32_16x16x32_bf16 v[114:117], v[152:155], v[192:195], v[114:117]
	v_mfma_f32_16x16x32_bf16 v[102:105], v[144:147], v[200:203], v[102:105]
	v_mfma_f32_16x16x32_bf16 v[98:101], v[152:155], v[200:203], v[98:101]
	v_mfma_f32_16x16x32_bf16 v[86:89], v[144:147], v[208:211], v[86:89]
	v_mfma_f32_16x16x32_bf16 v[82:85], v[152:155], v[208:211], v[82:85]
	v_mfma_f32_16x16x32_bf16 v[126:129], v[148:151], v[188:191], v[126:129]
	v_mfma_f32_16x16x32_bf16 v[122:125], v[156:159], v[188:191], v[122:125]
	v_mfma_f32_16x16x32_bf16 v[118:121], v[148:151], v[196:199], v[118:121]
	v_mfma_f32_16x16x32_bf16 v[114:117], v[156:159], v[196:199], v[114:117]
	v_mfma_f32_16x16x32_bf16 v[102:105], v[148:151], v[204:207], v[102:105]
	v_mfma_f32_16x16x32_bf16 v[98:101], v[156:159], v[204:207], v[98:101]
	v_mfma_f32_16x16x32_bf16 v[86:89], v[148:151], v[212:215], v[86:89]
	v_mfma_f32_16x16x32_bf16 v[82:85], v[156:159], v[212:215], v[82:85]
	s_setprio 0
	s_setprio 1
	v_mfma_f32_16x16x32_bf16 v[110:113], v[160:163], v[182:185], v[110:113]
	v_mfma_f32_16x16x32_bf16 v[106:109], v[168:171], v[182:185], v[106:109]
	v_mfma_f32_16x16x32_bf16 v[94:97], v[160:163], v[192:195], v[94:97]
	v_mfma_f32_16x16x32_bf16 v[90:93], v[168:171], v[192:195], v[90:93]
	v_mfma_f32_16x16x32_bf16 v[78:81], v[160:163], v[200:203], v[78:81]
	v_mfma_f32_16x16x32_bf16 v[74:77], v[168:171], v[200:203], v[74:77]
	v_mfma_f32_16x16x32_bf16 v[70:73], v[160:163], v[208:211], v[70:73]
	v_mfma_f32_16x16x32_bf16 v[66:69], v[168:171], v[208:211], v[66:69]
	v_mfma_f32_16x16x32_bf16 v[110:113], v[164:167], v[188:191], v[110:113]
	v_mfma_f32_16x16x32_bf16 v[106:109], v[176:179], v[188:191], v[106:109]
	v_mfma_f32_16x16x32_bf16 v[94:97], v[164:167], v[196:199], v[94:97]
	v_mfma_f32_16x16x32_bf16 v[90:93], v[176:179], v[196:199], v[90:93]
	v_mfma_f32_16x16x32_bf16 v[78:81], v[164:167], v[204:207], v[78:81]
	v_mfma_f32_16x16x32_bf16 v[74:77], v[176:179], v[204:207], v[74:77]
	v_mfma_f32_16x16x32_bf16 v[70:73], v[164:167], v[212:215], v[70:73]
	v_mfma_f32_16x16x32_bf16 v[66:69], v[176:179], v[212:215], v[66:69]
	s_setprio 0
	s_barrier
; #define G_STAGE(bufoff, gbase, voff) do { _Pragma("unroll") for (int _i = 0; _i < 2; ++_i) \
;         __builtin_amdgcn_global_load_lds((const unsigned*)((const char*)(gbase) + (voff)[_i]), (LAS unsigned*)(lds + (bufoff) + ldsw + _i * 8192), 16, 0, 0); } while (0)
; #define G_LDA(dst, b, h) do { _Pragma("unroll") for (int m = 0; m < 4; ++m) _Pragma("unroll") for (int k = 0; k < 2; ++k) dst[m][k] = *(const LAS bf16x8*)(lds + G_SA(b, h) + aoff + m * 2048 + k * 1024); } while (0)
; #define G_MMA(ai, bj, At, Bt_) do { __builtin_amdgcn_s_setprio(1); _Pragma("unroll") for (int m = 0; m < 4; ++m) _Pragma("unroll") for (int n = 0; n < 2; ++n) _Pragma("unroll") for (int k = 0; k < 2; ++k) \
;         acc[ai][bj][m][n] = __builtin_amdgcn_mfma_f32_16x16x32_bf16(Bt_[n][k], At[m][k], acc[ai][bj][m][n], 0, 0, 0); __builtin_amdgcn_s_setprio(0); } while (0)
; #define G_WAIT_V(n) asm volatile("s_waitcnt vmcnt(" #n ")" ::: "memory")
; #define G_WAIT_L(n) asm volatile("s_waitcnt lgkmcnt(" #n ")" ::: "memory")
; #define G_BAR __builtin_amdgcn_s_barrier()
; #define G_SCHED __builtin_amdgcn_sched_barrier(0)
; template <int NSTORE, class TF, class F>
; DEVI void gemm_run(const bf16_t* __restrict__ A, int lda, const bf16_t* __restrict__ Bt, int ldb, int K, bf16_t* shm, TF&& tile, F&& emit) {
;     ...
;             G_LDA(At, 1, 1); G_STAGE(G_SB(1, 0), b3, voffB); G_STAGE(G_SB(1, 1), b3 + hstepB, voffB); G_STAGE(G_SA(1, 0), a3, voffA);
;             G_WAIT_V(8); G_WAIT_L(0); G_BAR; G_MMA(1, 0, At, B0); G_MMA(1, 1, At, B1); G_BAR; G_SCHED;
;         }
	s_mov_b32 m0, s94
	v_lshl_add_u64 v[216:217], v[216:217], 0, s[30:31]
	s_add_u32 s28, s76, 0x100080
	ds_read_b128 v[182:185], v142 offset:49152
	ds_read_b128 v[188:191], v142 offset:50176
	ds_read_b128 v[192:195], v142 offset:51200
	ds_read_b128 v[196:199], v142 offset:52224
	ds_read_b128 v[200:203], v142 offset:53248
	ds_read_b128 v[204:207], v142 offset:54272
	ds_read_b128 v[208:211], v142 offset:55296
	ds_read_b128 v[212:215], v142 offset:56320
	global_load_lds_dwordx4 v[216:217], off
	v_lshl_add_u64 v[216:217], v[218:219], 0, s[30:31]
	s_mov_b32 m0, s95
	s_addc_u32 s29, s77, 0
	global_load_lds_dwordx4 v[216:217], off
	v_lshl_add_u64 v[216:217], s[28:29], 0, v[0:1]
	s_mov_b32 m0, s26
	s_nop 0
	global_load_lds_dwordx4 v[216:217], off
	v_lshl_add_u64 v[216:217], s[28:29], 0, v[134:135]
	s_mov_b32 m0, s27
	s_nop 0
	global_load_lds_dwordx4 v[216:217], off
	v_lshl_add_u64 v[216:217], v[220:221], 0, s[30:31]
	s_mov_b32 m0, s8
	s_nop 0
	global_load_lds_dwordx4 v[216:217], off
	v_lshl_add_u64 v[216:217], v[222:223], 0, s[30:31]
	s_mov_b32 m0, s9
	s_nop 0
	global_load_lds_dwordx4 v[216:217], off
	s_waitcnt vmcnt(8)
	s_waitcnt lgkmcnt(0)
	s_barrier
	s_setprio 1
	s_waitcnt lgkmcnt(0)
	v_mfma_f32_16x16x32_bf16 v[62:65], v[144:147], v[182:185], v[62:65]
	v_mfma_f32_16x16x32_bf16 v[58:61], v[152:155], v[182:185], v[58:61]
	v_mfma_f32_16x16x32_bf16 v[54:57], v[144:147], v[192:195], v[54:57]
	v_mfma_f32_16x16x32_bf16 v[50:53], v[152:155], v[192:195], v[50:53]
	v_mfma_f32_16x16x32_bf16 v[38:41], v[144:147], v[200:203], v[38:41]
	v_mfma_f32_16x16x32_bf16 v[34:37], v[152:155], v[200:203], v[34:37]
	v_mfma_f32_16x16x32_bf16 v[22:25], v[144:147], v[208:211], v[22:25]
	v_mfma_f32_16x16x32_bf16 v[18:21], v[152:155], v[208:211], v[18:21]
	v_mfma_f32_16x16x32_bf16 v[62:65], v[148:151], v[188:191], v[62:65]
	v_mfma_f32_16x16x32_bf16 v[58:61], v[156:159], v[188:191], v[58:61]
	v_mfma_f32_16x16x32_bf16 v[54:57], v[148:151], v[196:199], v[54:57]
	v_mfma_f32_16x16x32_bf16 v[50:53], v[156:159], v[196:199], v[50:53]
	v_mfma_f32_16x16x32_bf16 v[38:41], v[148:151], v[204:207], v[38:41]
	v_mfma_f32_16x16x32_bf16 v[34:37], v[156:159], v[204:207], v[34:37]
	v_mfma_f32_16x16x32_bf16 v[22:25], v[148:151], v[212:215], v[22:25]
	v_mfma_f32_16x16x32_bf16 v[18:21], v[156:159], v[212:215], v[18:21]
	s_setprio 0
	s_setprio 1
	v_mfma_f32_16x16x32_bf16 v[46:49], v[160:163], v[182:185], v[46:49]
	v_mfma_f32_16x16x32_bf16 v[42:45], v[168:171], v[182:185], v[42:45]
	v_mfma_f32_16x16x32_bf16 v[30:33], v[160:163], v[192:195], v[30:33]
	v_mfma_f32_16x16x32_bf16 v[26:29], v[168:171], v[192:195], v[26:29]
	v_mfma_f32_16x16x32_bf16 v[14:17], v[160:163], v[200:203], v[14:17]
	s_add_i32 s82, s82, 2
	v_mfma_f32_16x16x32_bf16 v[10:13], v[168:171], v[200:203], v[10:13]
	v_mfma_f32_16x16x32_bf16 v[6:9], v[160:163], v[208:211], v[6:9]
	s_add_u32 s74, s74, 0x100
	v_mfma_f32_16x16x32_bf16 v[2:5], v[168:171], v[208:211], v[2:5]
	v_mfma_f32_16x16x32_bf16 v[46:49], v[164:167], v[188:191], v[46:49]
	s_addc_u32 s75, s75, 0
	v_mfma_f32_16x16x32_bf16 v[42:45], v[176:179], v[188:191], v[42:45]
	v_mfma_f32_16x16x32_bf16 v[30:33], v[164:167], v[196:199], v[30:33]
	s_add_u32 s33, s33, 0x100
	v_mfma_f32_16x16x32_bf16 v[26:29], v[176:179], v[196:199], v[26:29]
	v_mfma_f32_16x16x32_bf16 v[14:17], v[164:167], v[204:207], v[14:17]
	s_addc_u32 s3, s3, 0
	v_mfma_f32_16x16x32_bf16 v[10:13], v[176:179], v[204:207], v[10:13]
	v_mfma_f32_16x16x32_bf16 v[6:9], v[164:167], v[212:215], v[6:9]
	s_cmp_gt_u32 s82, 61
	v_mfma_f32_16x16x32_bf16 v[2:5], v[176:179], v[212:215], v[2:5]
	s_setprio 0
	s_barrier
	s_cbranch_scc0 .LBB0_488
	s_and_b64 vcc, exec, s[40:41]
	s_cbranch_vccz .LBB0_491
	s_barrier

; #define G_STAGE(bufoff, gbase, voff) do { _Pragma("unroll") for (int _i = 0; _i < 2; ++_i) \
;         __builtin_amdgcn_global_load_lds((const unsigned*)((const char*)(gbase) + (voff)[_i]), (LAS unsigned*)(lds + (bufoff) + ldsw + _i * 8192), 16, 0, 0); } while (0)
; #define G_LDA(dst, b, h) do { _Pragma("unroll") for (int m = 0; m < 4; ++m) _Pragma("unroll") for (int k = 0; k < 2; ++k) dst[m][k] = *(const LAS bf16x8*)(lds + G_SA(b, h) + aoff + m * 2048 + k * 1024); } while (0)
; #define G_LDB(dst, b, h) do { _Pragma("unroll") for (int n = 0; n < 2; ++n) _Pragma("unroll") for (int k = 0; k < 2; ++k) dst[n][k] = *(const LAS bf16x8*)(lds + G_SB(b, h) + boff + n * 2048 + k * 1024); } while (0)
; #define G_MMA(ai, bj, At, Bt_) do { __builtin_amdgcn_s_setprio(1); _Pragma("unroll") for (int m = 0; m < 4; ++m) _Pragma("unroll") for (int n = 0; n < 2; ++n) _Pragma("unroll") for (int k = 0; k < 2; ++k) \
;         acc[ai][bj][m][n] = __builtin_amdgcn_mfma_f32_16x16x32_bf16(Bt_[n][k], At[m][k], acc[ai][bj][m][n], 0, 0, 0); __builtin_amdgcn_s_setprio(0); } while (0)
; #define G_WAIT_V(n) asm volatile("s_waitcnt vmcnt(" #n ")" ::: "memory")
; #define G_WAIT_L(n) asm volatile("s_waitcnt lgkmcnt(" #n ")" ::: "memory")
; #define G_BAR __builtin_amdgcn_s_barrier()
; #define G_SCHED __builtin_amdgcn_sched_barrier(0)
; template <int NSTORE, class TF, class F>
; DEVI void gemm_run(const bf16_t* __restrict__ A, int lda, const bf16_t* __restrict__ Bt, int ldb, int K, bf16_t* shm, TF&& tile, F&& emit) {
;     ...
;         for (int t = 0; t < nt; t += 2) {
;             const bool last = (t == nt - 2);
;             const char* a1 = cA + (size_t)(t + 1) * kstep;
;             const char* a2 = last ? nA : cA + (size_t)(t + 2) * kstep; const char* b2 = last ? nB : cB + (size_t)(t + 2) * kstep;
;             const char* a3 = a2 + kstep; const char* b3 = b2 + kstep;
;             G_LDB(B0, 0, 0); G_LDB(B1, 0, 1); G_SCHED; G_LDA(At, 0, 0); G_STAGE(G_SA(1, 1), a1 + hstepA, voffA);
;             G_WAIT_V(8); G_WAIT_L(0); G_BAR; G_MMA(0, 0, At, B0); G_MMA(0, 1, At, B1); G_BAR; G_SCHED;
;             G_LDA(At, 0, 1); G_STAGE(G_SB(0, 0), b2, voffB); G_STAGE(G_SB(0, 1), b2 + hstepB, voffB); G_STAGE(G_SA(0, 0), a2, voffA);
;             G_WAIT_V(8); G_WAIT_L(0); G_BAR; G_MMA(1, 0, At, B0); G_MMA(1, 1, At, B1); G_BAR; G_SCHED;
.LBB0_512:
	v_or_b32_e32 v140, 0x10000, v144
	v_add_u32_e32 v141, 0x10400, v144
	ds_read_b128 v[146:149], v140
	ds_read_b128 v[150:153], v141
	v_add_u32_e32 v140, 0x10800, v144
	v_add_u32_e32 v141, 0x10c00, v144
	ds_read_b128 v[154:157], v140
	ds_read_b128 v[158:161], v141
	v_or_b32_e32 v140, 0x14000, v144
	v_add_u32_e32 v141, 0x14400, v144
	ds_read_b128 v[162:165], v140
	ds_read_b128 v[166:169], v141
	v_add_u32_e32 v140, 0x14800, v144
	v_add_u32_e32 v141, 0x14c00, v144
	ds_read_b128 v[176:179], v140
	ds_read_b128 v[182:185], v141
	s_add_u32 s28, s68, 0xfffc0080
	s_addc_u32 s29, s69, -1
	s_cmp_eq_u32 s82, 12
	s_cselect_b32 s73, s39, s29
	s_cselect_b32 s72, s48, s28
	s_cselect_b32 s71, s41, s3
	s_cselect_b32 s70, s49, s33
	v_lshl_add_u64 v[140:141], s[68:69], 0, v[136:137]
	s_add_i32 m0, s74, 0xc000
	ds_read_b128 v[188:191], v143
	ds_read_b128 v[192:195], v143 offset:1024
	ds_read_b128 v[196:199], v143 offset:2048
	ds_read_b128 v[200:203], v143 offset:3072
	ds_read_b128 v[204:207], v143 offset:4096
	ds_read_b128 v[208:211], v143 offset:5120
	ds_read_b128 v[212:215], v143 offset:6144
	ds_read_b128 v[216:219], v143 offset:7168
	global_load_lds_dwordx4 v[140:141], off
	v_lshl_add_u64 v[140:141], s[68:69], 0, v[138:139]
	s_add_i32 m0, s74, 0xe000
	s_nop 0
	global_load_lds_dwordx4 v[140:141], off
	s_waitcnt vmcnt(8)
	s_waitcnt lgkmcnt(0)
	s_barrier
	s_setprio 1
	s_waitcnt lgkmcnt(0)
	v_mfma_f32_16x16x32_bf16 v[126:129], v[146:149], v[188:191], v[126:129]
	v_mfma_f32_16x16x32_bf16 v[122:125], v[154:157], v[188:191], v[122:125]
	v_mfma_f32_16x16x32_bf16 v[110:113], v[146:149], v[196:199], v[110:113]
	v_mfma_f32_16x16x32_bf16 v[106:109], v[154:157], v[196:199], v[106:109]
	v_mfma_f32_16x16x32_bf16 v[94:97], v[146:149], v[204:207], v[94:97]
	v_mfma_f32_16x16x32_bf16 v[90:93], v[154:157], v[204:207], v[90:93]
	v_mfma_f32_16x16x32_bf16 v[78:81], v[146:149], v[212:215], v[78:81]
	v_mfma_f32_16x16x32_bf16 v[74:77], v[154:157], v[212:215], v[74:77]
	v_mfma_f32_16x16x32_bf16 v[126:129], v[150:153], v[192:195], v[126:129]
	v_mfma_f32_16x16x32_bf16 v[122:125], v[158:161], v[192:195], v[122:125]
	v_mfma_f32_16x16x32_bf16 v[110:113], v[150:153], v[200:203], v[110:113]
	v_mfma_f32_16x16x32_bf16 v[106:109], v[158:161], v[200:203], v[106:109]
	v_mfma_f32_16x16x32_bf16 v[94:97], v[150:153], v[208:211], v[94:97]
	v_mfma_f32_16x16x32_bf16 v[90:93], v[158:161], v[208:211], v[90:93]
	v_mfma_f32_16x16x32_bf16 v[78:81], v[150:153], v[216:219], v[78:81]
	v_mfma_f32_16x16x32_bf16 v[74:77], v[158:161], v[216:219], v[74:77]
	s_setprio 0
	s_setprio 1
	v_mfma_f32_16x16x32_bf16 v[118:121], v[162:165], v[188:191], v[118:121]
	v_mfma_f32_16x16x32_bf16 v[114:117], v[176:179], v[188:191], v[114:117]
	v_mfma_f32_16x16x32_bf16 v[102:105], v[162:165], v[196:199], v[102:105]
	v_mfma_f32_16x16x32_bf16 v[98:101], v[176:179], v[196:199], v[98:101]
	v_mfma_f32_16x16x32_bf16 v[86:89], v[162:165], v[204:207], v[86:89]
	v_mfma_f32_16x16x32_bf16 v[82:85], v[176:179], v[204:207], v[82:85]
	v_mfma_f32_16x16x32_bf16 v[70:73], v[162:165], v[212:215], v[70:73]
	v_mfma_f32_16x16x32_bf16 v[66:69], v[176:179], v[212:215], v[66:69]
	v_mfma_f32_16x16x32_bf16 v[118:121], v[166:169], v[192:195], v[118:121]
	v_mfma_f32_16x16x32_bf16 v[114:117], v[182:185], v[192:195], v[114:117]
	v_mfma_f32_16x16x32_bf16 v[102:105], v[166:169], v[200:203], v[102:105]
	v_mfma_f32_16x16x32_bf16 v[98:101], v[182:185], v[200:203], v[98:101]
	v_mfma_f32_16x16x32_bf16 v[86:89], v[166:169], v[208:211], v[86:89]
	v_mfma_f32_16x16x32_bf16 v[82:85], v[182:185], v[208:211], v[82:85]
	v_mfma_f32_16x16x32_bf16 v[70:73], v[166:169], v[216:219], v[70:73]
	v_mfma_f32_16x16x32_bf16 v[66:69], v[182:185], v[216:219], v[66:69]
	s_setprio 0
	s_barrier
	s_mov_b32 m0, s75
	v_lshl_add_u64 v[140:141], s[70:71], 0, v[0:1]
	s_add_u32 s28, s70, 0x40000
	ds_read_b128 v[188:191], v143 offset:16384
	ds_read_b128 v[192:195], v143 offset:17408
	ds_read_b128 v[196:199], v143 offset:18432
	ds_read_b128 v[200:203], v143 offset:19456
	ds_read_b128 v[204:207], v143 offset:20480
	ds_read_b128 v[208:211], v143 offset:21504
	ds_read_b128 v[212:215], v143 offset:22528
	ds_read_b128 v[216:219], v143 offset:23552
	global_load_lds_dwordx4 v[140:141], off
	v_lshl_add_u64 v[170:171], s[70:71], 0, v[130:131]
	s_mov_b32 m0, s76
	s_addc_u32 s29, s71, 0
	global_load_lds_dwordx4 v[170:171], off
	v_lshl_add_u64 v[220:221], s[28:29], 0, v[0:1]
	s_mov_b32 m0, s77
	v_lshl_add_u64 v[222:223], s[72:73], 0, v[132:133]
	global_load_lds_dwordx4 v[220:221], off
	v_lshl_add_u64 v[220:221], s[28:29], 0, v[130:131]
	s_mov_b32 m0, s78
	s_nop 0
	global_load_lds_dwordx4 v[220:221], off
	v_lshl_add_u64 v[220:221], s[72:73], 0, v[134:135]
	s_mov_b32 m0, s74
	s_nop 0
	global_load_lds_dwordx4 v[220:221], off
	s_mov_b32 m0, s79
	s_nop 0
	global_load_lds_dwordx4 v[222:223], off
	s_waitcnt vmcnt(8)
	s_waitcnt lgkmcnt(0)
	s_barrier
; #define G_STAGE(bufoff, gbase, voff) do { _Pragma("unroll") for (int _i = 0; _i < 2; ++_i) \
;         __builtin_amdgcn_global_load_lds((const unsigned*)((const char*)(gbase) + (voff)[_i]), (LAS unsigned*)(lds + (bufoff) + ldsw + _i * 8192), 16, 0, 0); } while (0)
; #define G_LDA(dst, b, h) do { _Pragma("unroll") for (int m = 0; m < 4; ++m) _Pragma("unroll") for (int k = 0; k < 2; ++k) dst[m][k] = *(const LAS bf16x8*)(lds + G_SA(b, h) + aoff + m * 2048 + k * 1024); } while (0)
; #define G_LDB(dst, b, h) do { _Pragma("unroll") for (int n = 0; n < 2; ++n) _Pragma("unroll") for (int k = 0; k < 2; ++k) dst[n][k] = *(const LAS bf16x8*)(lds + G_SB(b, h) + boff + n * 2048 + k * 1024); } while (0)
; #define G_MMA(ai, bj, At, Bt_) do { __builtin_amdgcn_s_setprio(1); _Pragma("unroll") for (int m = 0; m < 4; ++m) _Pragma("unroll") for (int n = 0; n < 2; ++n) _Pragma("unroll") for (int k = 0; k < 2; ++k) \
;         acc[ai][bj][m][n] = __builtin_amdgcn_mfma_f32_16x16x32_bf16(Bt_[n][k], At[m][k], acc[ai][bj][m][n], 0, 0, 0); __builtin_amdgcn_s_setprio(0); } while (0)
; #define G_WAIT_V(n) asm volatile("s_waitcnt vmcnt(" #n ")" ::: "memory")
; #define G_WAIT_L(n) asm volatile("s_waitcnt lgkmcnt(" #n ")" ::: "memory")
; #define G_BAR __builtin_amdgcn_s_barrier()
; #define G_SCHED __builtin_amdgcn_sched_barrier(0)
; template <int NSTORE, class TF, class F>
; DEVI void gemm_run(const bf16_t* __restrict__ A, int lda, const bf16_t* __restrict__ Bt, int ldb, int K, bf16_t* shm, TF&& tile, F&& emit) {
;     ...
;             G_WAIT_V(8); G_WAIT_L(0); G_BAR; G_MMA(0, 0, At, B0); G_MMA(0, 1, At, B1); G_BAR; G_SCHED;
;             G_LDA(At, 0, 1); G_STAGE(G_SB(0, 0), b2, voffB); G_STAGE(G_SB(0, 1), b2 + hstepB, voffB); G_STAGE(G_SA(0, 0), a2, voffA);
;             G_WAIT_V(8); G_WAIT_L(0); G_BAR; G_MMA(1, 0, At, B0); G_MMA(1, 1, At, B1); G_BAR; G_SCHED;
;             G_LDB(B0, 1, 0); G_LDB(B1, 1, 1); G_SCHED; G_LDA(At, 1, 0); G_STAGE(G_SA(0, 1), a2 + hstepA, voffA);
;             G_WAIT_V(8); G_WAIT_L(0); G_BAR; G_MMA(0, 0, At, B0); G_MMA(0, 1, At, B1); G_BAR; G_SCHED;
	s_setprio 1
	s_waitcnt lgkmcnt(0)
	v_mfma_f32_16x16x32_bf16 v[62:65], v[146:149], v[188:191], v[62:65]
	v_mfma_f32_16x16x32_bf16 v[58:61], v[154:157], v[188:191], v[58:61]
	v_mfma_f32_16x16x32_bf16 v[46:49], v[146:149], v[196:199], v[46:49]
	v_mfma_f32_16x16x32_bf16 v[42:45], v[154:157], v[196:199], v[42:45]
	v_mfma_f32_16x16x32_bf16 v[30:33], v[146:149], v[204:207], v[30:33]
	v_mfma_f32_16x16x32_bf16 v[26:29], v[154:157], v[204:207], v[26:29]
	v_mfma_f32_16x16x32_bf16 v[14:17], v[146:149], v[212:215], v[14:17]
	v_mfma_f32_16x16x32_bf16 v[10:13], v[154:157], v[212:215], v[10:13]
	v_mfma_f32_16x16x32_bf16 v[62:65], v[150:153], v[192:195], v[62:65]
	v_mfma_f32_16x16x32_bf16 v[58:61], v[158:161], v[192:195], v[58:61]
	v_mfma_f32_16x16x32_bf16 v[46:49], v[150:153], v[200:203], v[46:49]
	v_mfma_f32_16x16x32_bf16 v[42:45], v[158:161], v[200:203], v[42:45]
	v_mfma_f32_16x16x32_bf16 v[30:33], v[150:153], v[208:211], v[30:33]
	v_mfma_f32_16x16x32_bf16 v[26:29], v[158:161], v[208:211], v[26:29]
	v_mfma_f32_16x16x32_bf16 v[14:17], v[150:153], v[216:219], v[14:17]
	v_mfma_f32_16x16x32_bf16 v[10:13], v[158:161], v[216:219], v[10:13]
	s_setprio 0
	s_setprio 1
	v_mfma_f32_16x16x32_bf16 v[54:57], v[162:165], v[188:191], v[54:57]
	v_mfma_f32_16x16x32_bf16 v[50:53], v[176:179], v[188:191], v[50:53]
	v_mfma_f32_16x16x32_bf16 v[38:41], v[162:165], v[196:199], v[38:41]
	v_mfma_f32_16x16x32_bf16 v[34:37], v[176:179], v[196:199], v[34:37]
	v_mfma_f32_16x16x32_bf16 v[22:25], v[162:165], v[204:207], v[22:25]
	v_mfma_f32_16x16x32_bf16 v[18:21], v[176:179], v[204:207], v[18:21]
	v_mfma_f32_16x16x32_bf16 v[6:9], v[162:165], v[212:215], v[6:9]
	v_mfma_f32_16x16x32_bf16 v[2:5], v[176:179], v[212:215], v[2:5]
	v_mfma_f32_16x16x32_bf16 v[54:57], v[166:169], v[192:195], v[54:57]
	v_mfma_f32_16x16x32_bf16 v[50:53], v[182:185], v[192:195], v[50:53]
	v_mfma_f32_16x16x32_bf16 v[38:41], v[166:169], v[200:203], v[38:41]
	v_mfma_f32_16x16x32_bf16 v[34:37], v[182:185], v[200:203], v[34:37]
	v_mfma_f32_16x16x32_bf16 v[22:25], v[166:169], v[208:211], v[22:25]
	v_mfma_f32_16x16x32_bf16 v[18:21], v[182:185], v[208:211], v[18:21]
	v_mfma_f32_16x16x32_bf16 v[6:9], v[166:169], v[216:219], v[6:9]
	v_mfma_f32_16x16x32_bf16 v[2:5], v[182:185], v[216:219], v[2:5]
	s_setprio 0
	s_barrier
	v_or_b32_e32 v146, 0x18000, v144
	v_add_u32_e32 v150, 0x18400, v144
	v_add_u32_e32 v154, 0x18800, v144
	v_add_u32_e32 v158, 0x18c00, v144
	v_or_b32_e32 v162, 0x1c000, v144
	v_add_u32_e32 v166, 0x1c400, v144
	v_add_u32_e32 v176, 0x1c800, v144
	v_add_u32_e32 v182, 0x1cc00, v144
	ds_read_b128 v[146:149], v146
	ds_read_b128 v[150:153], v150
	ds_read_b128 v[154:157], v154
	ds_read_b128 v[158:161], v158
	ds_read_b128 v[162:165], v162
	ds_read_b128 v[166:169], v166
	ds_read_b128 v[176:179], v176
	ds_read_b128 v[182:185], v182
	s_add_u32 s28, s72, 0x40000
	s_addc_u32 s29, s73, 0
	s_mov_b32 m0, s95
	v_lshl_add_u64 v[224:225], s[28:29], 0, v[134:135]
	ds_read_b128 v[188:191], v143 offset:32768
	ds_read_b128 v[192:195], v143 offset:33792
	ds_read_b128 v[196:199], v143 offset:34816
	ds_read_b128 v[200:203], v143 offset:35840
	ds_read_b128 v[204:207], v143 offset:36864
	ds_read_b128 v[208:211], v143 offset:37888
	ds_read_b128 v[212:215], v143 offset:38912
	ds_read_b128 v[216:219], v143 offset:39936
	global_load_lds_dwordx4 v[224:225], off
	v_lshl_add_u64 v[224:225], s[28:29], 0, v[132:133]
	s_mov_b32 m0, s18
	s_nop 0
	global_load_lds_dwordx4 v[224:225], off
	s_waitcnt vmcnt(8)
	s_waitcnt lgkmcnt(0)
	s_barrier
	s_setprio 1
	s_waitcnt lgkmcnt(0)
	v_mfma_f32_16x16x32_bf16 v[126:129], v[146:149], v[188:191], v[126:129]
	v_mfma_f32_16x16x32_bf16 v[122:125], v[154:157], v[188:191], v[122:125]
	v_mfma_f32_16x16x32_bf16 v[110:113], v[146:149], v[196:199], v[110:113]
	v_mfma_f32_16x16x32_bf16 v[106:109], v[154:157], v[196:199], v[106:109]
	v_mfma_f32_16x16x32_bf16 v[94:97], v[146:149], v[204:207], v[94:97]
	v_mfma_f32_16x16x32_bf16 v[90:93], v[154:157], v[204:207], v[90:93]
	v_mfma_f32_16x16x32_bf16 v[78:81], v[146:149], v[212:215], v[78:81]
	v_mfma_f32_16x16x32_bf16 v[74:77], v[154:157], v[212:215], v[74:77]
	v_mfma_f32_16x16x32_bf16 v[126:129], v[150:153], v[192:195], v[126:129]
	v_mfma_f32_16x16x32_bf16 v[122:125], v[158:161], v[192:195], v[122:125]
	v_mfma_f32_16x16x32_bf16 v[110:113], v[150:153], v[200:203], v[110:113]
	v_mfma_f32_16x16x32_bf16 v[106:109], v[158:161], v[200:203], v[106:109]
	v_mfma_f32_16x16x32_bf16 v[94:97], v[150:153], v[208:211], v[94:97]
	v_mfma_f32_16x16x32_bf16 v[90:93], v[158:161], v[208:211], v[90:93]
	v_mfma_f32_16x16x32_bf16 v[78:81], v[150:153], v[216:219], v[78:81]
	v_mfma_f32_16x16x32_bf16 v[74:77], v[158:161], v[216:219], v[74:77]
	s_setprio 0
	s_setprio 1
	v_mfma_f32_16x16x32_bf16 v[118:121], v[162:165], v[188:191], v[118:121]
	v_mfma_f32_16x16x32_bf16 v[114:117], v[176:179], v[188:191], v[114:117]
	v_mfma_f32_16x16x32_bf16 v[102:105], v[162:165], v[196:199], v[102:105]
	v_mfma_f32_16x16x32_bf16 v[98:101], v[176:179], v[196:199], v[98:101]
	v_mfma_f32_16x16x32_bf16 v[86:89], v[162:165], v[204:207], v[86:89]
	v_mfma_f32_16x16x32_bf16 v[82:85], v[176:179], v[204:207], v[82:85]
	v_mfma_f32_16x16x32_bf16 v[70:73], v[162:165], v[212:215], v[70:73]
	v_mfma_f32_16x16x32_bf16 v[66:69], v[176:179], v[212:215], v[66:69]
	v_mfma_f32_16x16x32_bf16 v[118:121], v[166:169], v[192:195], v[118:121]
	v_mfma_f32_16x16x32_bf16 v[114:117], v[182:185], v[192:195], v[114:117]
	v_mfma_f32_16x16x32_bf16 v[102:105], v[166:169], v[200:203], v[102:105]
	v_mfma_f32_16x16x32_bf16 v[98:101], v[182:185], v[200:203], v[98:101]
	v_mfma_f32_16x16x32_bf16 v[86:89], v[166:169], v[208:211], v[86:89]
	v_mfma_f32_16x16x32_bf16 v[82:85], v[182:185], v[208:211], v[82:85]
	v_mfma_f32_16x16x32_bf16 v[70:73], v[166:169], v[216:219], v[70:73]
	v_mfma_f32_16x16x32_bf16 v[66:69], v[182:185], v[216:219], v[66:69]
	s_setprio 0
	s_barrier
; #define G_STAGE(bufoff, gbase, voff) do { _Pragma("unroll") for (int _i = 0; _i < 2; ++_i) \
;         __builtin_amdgcn_global_load_lds((const unsigned*)((const char*)(gbase) + (voff)[_i]), (LAS unsigned*)(lds + (bufoff) + ldsw + _i * 8192), 16, 0, 0); } while (0)
; #define G_LDA(dst, b, h) do { _Pragma("unroll") for (int m = 0; m < 4; ++m) _Pragma("unroll") for (int k = 0; k < 2; ++k) dst[m][k] = *(const LAS bf16x8*)(lds + G_SA(b, h) + aoff + m * 2048 + k * 1024); } while (0)
; #define G_LDB(dst, b, h) do { _Pragma("unroll") for (int n = 0; n < 2; ++n) _Pragma("unroll") for (int k = 0; k < 2; ++k) dst[n][k] = *(const LAS bf16x8*)(lds + G_SB(b, h) + boff + n * 2048 + k * 1024); } while (0)
; #define G_WAIT_V(n) asm volatile("s_waitcnt vmcnt(" #n ")" ::: "memory")
; #define G_WAIT_L(n) asm volatile("s_waitcnt lgkmcnt(" #n ")" ::: "memory")
; #define G_BAR __builtin_amdgcn_s_barrier()
; template <int NSTORE, class TF, class F>
; DEVI void gemm_run(const bf16_t* __restrict__ A, int lda, const bf16_t* __restrict__ Bt, int ldb, int K, bf16_t* shm, TF&& tile, F&& emit) {
;     ...
;         for (int t = 0; t < nt; t += 2) {
;             const bool last = (t == nt - 2);
;             const char* a1 = cA + (size_t)(t + 1) * kstep;
;             const char* a2 = last ? nA : cA + (size_t)(t + 2) * kstep; const char* b2 = last ? nB : cB + (size_t)(t + 2) * kstep;
;             const char* a3 = a2 + kstep; const char* b3 = b2 + kstep;
;             G_LDB(B0, 0, 0); G_LDB(B1, 0, 1); G_SCHED; G_LDA(At, 0, 0); G_STAGE(G_SA(1, 1), a1 + hstepA, voffA);
;             G_WAIT_V(8); G_WAIT_L(0); G_BAR; G_MMA(0, 0, At, B0); G_MMA(0, 1, At, B1); G_BAR; G_SCHED;
;             G_LDA(At, 0, 1); G_STAGE(G_SB(0, 0), b2, voffB); G_STAGE(G_SB(0, 1), b2 + hstepB, voffB); G_STAGE(G_SA(0, 0), a2, voffA);
;             G_WAIT_V(8); G_WAIT_L(0); G_BAR; G_MMA(1, 0, At, B0); G_MMA(1, 1, At, B1); G_BAR; G_SCHED;
;             G_LDB(B0, 1, 0); G_LDB(B1, 1, 1); G_SCHED; G_LDA(At, 1, 0); G_STAGE(G_SA(0, 1), a2 + hstepA, voffA);
;             G_WAIT_V(8); G_WAIT_L(0); G_BAR; G_MMA(0, 0, At, B0); G_MMA(0, 1, At, B1); G_BAR; G_SCHED;
;             G_LDA(At, 1, 1); G_STAGE(G_SB(1, 0), b3, voffB); G_STAGE(G_SB(1, 1), b3 + hstepB, voffB); G_STAGE(G_SA(1, 0), a3, voffA);
;             G_WAIT_V(8); G_WAIT_L(0); G_BAR; G_MMA(1, 0, At, B0); G_MMA(1, 1, At, B1); G_BAR; G_SCHED;
	s_mov_b32 m0, s19
	v_lshl_add_u64 v[140:141], v[140:141], 0, s[30:31]
	s_add_u32 s28, s70, 0x40080
	ds_read_b128 v[188:191], v143 offset:49152
	ds_read_b128 v[192:195], v143 offset:50176
	ds_read_b128 v[196:199], v143 offset:51200
	ds_read_b128 v[200:203], v143 offset:52224
	ds_read_b128 v[204:207], v143 offset:53248
	ds_read_b128 v[208:211], v143 offset:54272
	ds_read_b128 v[212:215], v143 offset:55296
	ds_read_b128 v[216:219], v143 offset:56320
	global_load_lds_dwordx4 v[140:141], off
	v_lshl_add_u64 v[140:141], v[170:171], 0, s[30:31]
	s_mov_b32 m0, s14
	s_addc_u32 s29, s71, 0
	global_load_lds_dwordx4 v[140:141], off
	v_lshl_add_u64 v[140:141], s[28:29], 0, v[0:1]
	s_mov_b32 m0, s17
	s_nop 0
	global_load_lds_dwordx4 v[140:141], off
	v_lshl_add_u64 v[140:141], s[28:29], 0, v[130:131]
	s_mov_b32 m0, s94
	s_nop 0
	global_load_lds_dwordx4 v[140:141], off
	v_lshl_add_u64 v[140:141], v[220:221], 0, s[30:31]
	s_mov_b32 m0, s15
	s_nop 0
	global_load_lds_dwordx4 v[140:141], off
	v_lshl_add_u64 v[140:141], v[222:223], 0, s[30:31]
	s_mov_b32 m0, s16
	s_nop 0
	global_load_lds_dwordx4 v[140:141], off
	s_waitcnt vmcnt(8)
	s_waitcnt lgkmcnt(0)
	s_barrier
	s_setprio 1
	s_waitcnt lgkmcnt(0)
	v_mfma_f32_16x16x32_bf16 v[62:65], v[146:149], v[188:191], v[62:65]
	v_mfma_f32_16x16x32_bf16 v[58:61], v[154:157], v[188:191], v[58:61]
	v_mfma_f32_16x16x32_bf16 v[46:49], v[146:149], v[196:199], v[46:49]
	v_mfma_f32_16x16x32_bf16 v[42:45], v[154:157], v[196:199], v[42:45]
	v_mfma_f32_16x16x32_bf16 v[30:33], v[146:149], v[204:207], v[30:33]
	v_mfma_f32_16x16x32_bf16 v[26:29], v[154:157], v[204:207], v[26:29]
	v_mfma_f32_16x16x32_bf16 v[14:17], v[146:149], v[212:215], v[14:17]
	v_mfma_f32_16x16x32_bf16 v[10:13], v[154:157], v[212:215], v[10:13]
	v_mfma_f32_16x16x32_bf16 v[62:65], v[150:153], v[192:195], v[62:65]
	v_mfma_f32_16x16x32_bf16 v[58:61], v[158:161], v[192:195], v[58:61]
	v_mfma_f32_16x16x32_bf16 v[46:49], v[150:153], v[200:203], v[46:49]
	v_mfma_f32_16x16x32_bf16 v[42:45], v[158:161], v[200:203], v[42:45]
	v_mfma_f32_16x16x32_bf16 v[30:33], v[150:153], v[208:211], v[30:33]
	v_mfma_f32_16x16x32_bf16 v[26:29], v[158:161], v[208:211], v[26:29]
	v_mfma_f32_16x16x32_bf16 v[14:17], v[150:153], v[216:219], v[14:17]
	v_mfma_f32_16x16x32_bf16 v[10:13], v[158:161], v[216:219], v[10:13]
	s_setprio 0
	s_setprio 1
	v_mfma_f32_16x16x32_bf16 v[54:57], v[162:165], v[188:191], v[54:57]
	v_mfma_f32_16x16x32_bf16 v[50:53], v[176:179], v[188:191], v[50:53]
	v_mfma_f32_16x16x32_bf16 v[38:41], v[162:165], v[196:199], v[38:41]
	v_mfma_f32_16x16x32_bf16 v[34:37], v[176:179], v[196:199], v[34:37]
	v_mfma_f32_16x16x32_bf16 v[22:25], v[162:165], v[204:207], v[22:25]
	s_add_i32 s82, s82, 2
	v_mfma_f32_16x16x32_bf16 v[18:21], v[176:179], v[204:207], v[18:21]
	v_mfma_f32_16x16x32_bf16 v[6:9], v[162:165], v[212:215], v[6:9]
	s_add_u32 s68, s68, 0x100
	v_mfma_f32_16x16x32_bf16 v[2:5], v[176:179], v[212:215], v[2:5]
	v_mfma_f32_16x16x32_bf16 v[54:57], v[166:169], v[192:195], v[54:57]
	s_addc_u32 s69, s69, 0
	v_mfma_f32_16x16x32_bf16 v[50:53], v[182:185], v[192:195], v[50:53]
	v_mfma_f32_16x16x32_bf16 v[38:41], v[166:169], v[200:203], v[38:41]
	s_add_u32 s33, s33, 0x100
	v_mfma_f32_16x16x32_bf16 v[34:37], v[182:185], v[200:203], v[34:37]
	v_mfma_f32_16x16x32_bf16 v[22:25], v[166:169], v[208:211], v[22:25]
	s_addc_u32 s3, s3, 0
	v_mfma_f32_16x16x32_bf16 v[18:21], v[182:185], v[208:211], v[18:21]
	v_mfma_f32_16x16x32_bf16 v[6:9], v[166:169], v[216:219], v[6:9]
	s_cmp_gt_u32 s82, 13
	v_mfma_f32_16x16x32_bf16 v[2:5], v[182:185], v[216:219], v[2:5]
	s_setprio 0
	s_barrier
	s_cbranch_scc0 .LBB0_512
	s_and_b64 vcc, exec, s[8:9]
	s_cbranch_vccz .LBB0_515
	s_barrier

; #define G_STAGE(bufoff, gbase, voff) do { _Pragma("unroll") for (int _i = 0; _i < 2; ++_i) \
;         __builtin_amdgcn_global_load_lds((const unsigned*)((const char*)(gbase) + (voff)[_i]), (LAS unsigned*)(lds + (bufoff) + ldsw + _i * 8192), 16, 0, 0); } while (0)
; #define G_LDA(dst, b, h) do { _Pragma("unroll") for (int m = 0; m < 4; ++m) _Pragma("unroll") for (int k = 0; k < 2; ++k) dst[m][k] = *(const LAS bf16x8*)(lds + G_SA(b, h) + aoff + m * 2048 + k * 1024); } while (0)
; #define G_LDB(dst, b, h) do { _Pragma("unroll") for (int n = 0; n < 2; ++n) _Pragma("unroll") for (int k = 0; k < 2; ++k) dst[n][k] = *(const LAS bf16x8*)(lds + G_SB(b, h) + boff + n * 2048 + k * 1024); } while (0)
; #define G_MMA(ai, bj, At, Bt_) do { __builtin_amdgcn_s_setprio(1); _Pragma("unroll") for (int m = 0; m < 4; ++m) _Pragma("unroll") for (int n = 0; n < 2; ++n) _Pragma("unroll") for (int k = 0; k < 2; ++k) \
;         acc[ai][bj][m][n] = __builtin_amdgcn_mfma_f32_16x16x32_bf16(Bt_[n][k], At[m][k], acc[ai][bj][m][n], 0, 0, 0); __builtin_amdgcn_s_setprio(0); } while (0)
; #define G_WAIT_V(n) asm volatile("s_waitcnt vmcnt(" #n ")" ::: "memory")
; #define G_WAIT_L(n) asm volatile("s_waitcnt lgkmcnt(" #n ")" ::: "memory")
; #define G_BAR __builtin_amdgcn_s_barrier()
; template <int NSTORE, class TF, class F>
; DEVI void gemm_run(const bf16_t* __restrict__ A, int lda, const bf16_t* __restrict__ Bt, int ldb, int K, bf16_t* shm, TF&& tile, F&& emit) {
;     ...
;         const bool has_next = tile(ui + 1, nrow, ncol);
;         const char* nA = has_next ? (const char*)A + (size_t)nrow * lda * 2 : cA; const char* nB = has_next ? (const char*)Bt + (size_t)ncol * ldb * 2 : cB;
;         for (int t = 0; t < nt; t += 2) {
;             const bool last = (t == nt - 2);
;             const char* a1 = cA + (size_t)(t + 1) * kstep;
;             const char* a2 = last ? nA : cA + (size_t)(t + 2) * kstep; const char* b2 = last ? nB : cB + (size_t)(t + 2) * kstep;
;             const char* a3 = a2 + kstep; const char* b3 = b2 + kstep;
;             G_LDB(B0, 0, 0); G_LDB(B1, 0, 1); G_SCHED; G_LDA(At, 0, 0); G_STAGE(G_SA(1, 1), a1 + hstepA, voffA);
;             G_WAIT_V(8); G_WAIT_L(0); G_BAR; G_MMA(0, 0, At, B0); G_MMA(0, 1, At, B1); G_BAR; G_SCHED;
;             G_LDA(At, 0, 1); G_STAGE(G_SB(0, 0), b2, voffB); G_STAGE(G_SB(0, 1), b2 + hstepB, voffB); G_STAGE(G_SA(0, 0), a2, voffA);
.LBB0_545:
	v_or_b32_e32 v144, 0x10000, v142
	v_add_u32_e32 v148, 0x10400, v142
	v_add_u32_e32 v152, 0x10800, v142
	v_add_u32_e32 v156, 0x10c00, v142
	v_or_b32_e32 v160, 0x14000, v142
	v_add_u32_e32 v164, 0x14400, v142
	v_add_u32_e32 v168, 0x14800, v142
	v_add_u32_e32 v176, 0x14c00, v142
	ds_read_b128 v[144:147], v144
	ds_read_b128 v[148:151], v148
	ds_read_b128 v[152:155], v152
	ds_read_b128 v[156:159], v156
	ds_read_b128 v[160:163], v160
	ds_read_b128 v[164:167], v164
	ds_read_b128 v[168:171], v168
	ds_read_b128 v[176:179], v176
	s_add_u32 s28, s44, 0xfffc0080
	s_addc_u32 s29, s45, -1
	s_cmp_eq_u32 s82, 12
	s_cselect_b32 s69, s17, s29
	s_cselect_b32 s68, vcc_lo, s28
	s_cselect_b32 s47, s19, s3
	s_cselect_b32 s46, vcc_hi, s33
	v_lshl_add_u64 v[216:217], s[44:45], 0, v[136:137]
	s_add_i32 m0, s70, 0xc000
	ds_read_b128 v[182:185], v141
	ds_read_b128 v[188:191], v141 offset:1024
	ds_read_b128 v[192:195], v141 offset:2048
	ds_read_b128 v[196:199], v141 offset:3072
	ds_read_b128 v[200:203], v141 offset:4096
	ds_read_b128 v[204:207], v141 offset:5120
	ds_read_b128 v[208:211], v141 offset:6144
	ds_read_b128 v[212:215], v141 offset:7168
	global_load_lds_dwordx4 v[216:217], off
	v_lshl_add_u64 v[216:217], s[44:45], 0, v[138:139]
	s_add_i32 m0, s70, 0xe000
	s_nop 0
	global_load_lds_dwordx4 v[216:217], off
	s_waitcnt vmcnt(8)
	s_waitcnt lgkmcnt(0)
	s_barrier
	s_setprio 1
	s_waitcnt lgkmcnt(0)
	v_mfma_f32_16x16x32_bf16 v[126:129], v[144:147], v[182:185], v[126:129]
	v_mfma_f32_16x16x32_bf16 v[122:125], v[152:155], v[182:185], v[122:125]
	v_mfma_f32_16x16x32_bf16 v[118:121], v[144:147], v[192:195], v[118:121]
	v_mfma_f32_16x16x32_bf16 v[114:117], v[152:155], v[192:195], v[114:117]
	v_mfma_f32_16x16x32_bf16 v[102:105], v[144:147], v[200:203], v[102:105]
	v_mfma_f32_16x16x32_bf16 v[98:101], v[152:155], v[200:203], v[98:101]
	v_mfma_f32_16x16x32_bf16 v[86:89], v[144:147], v[208:211], v[86:89]
	v_mfma_f32_16x16x32_bf16 v[82:85], v[152:155], v[208:211], v[82:85]
	v_mfma_f32_16x16x32_bf16 v[126:129], v[148:151], v[188:191], v[126:129]
	v_mfma_f32_16x16x32_bf16 v[122:125], v[156:159], v[188:191], v[122:125]
	v_mfma_f32_16x16x32_bf16 v[118:121], v[148:151], v[196:199], v[118:121]
	v_mfma_f32_16x16x32_bf16 v[114:117], v[156:159], v[196:199], v[114:117]
	v_mfma_f32_16x16x32_bf16 v[102:105], v[148:151], v[204:207], v[102:105]
	v_mfma_f32_16x16x32_bf16 v[98:101], v[156:159], v[204:207], v[98:101]
	v_mfma_f32_16x16x32_bf16 v[86:89], v[148:151], v[212:215], v[86:89]
	v_mfma_f32_16x16x32_bf16 v[82:85], v[156:159], v[212:215], v[82:85]
	s_setprio 0
	s_setprio 1
	v_mfma_f32_16x16x32_bf16 v[110:113], v[160:163], v[182:185], v[110:113]
	v_mfma_f32_16x16x32_bf16 v[106:109], v[168:171], v[182:185], v[106:109]
	v_mfma_f32_16x16x32_bf16 v[94:97], v[160:163], v[192:195], v[94:97]
	v_mfma_f32_16x16x32_bf16 v[90:93], v[168:171], v[192:195], v[90:93]
	v_mfma_f32_16x16x32_bf16 v[78:81], v[160:163], v[200:203], v[78:81]
	v_mfma_f32_16x16x32_bf16 v[74:77], v[168:171], v[200:203], v[74:77]
	v_mfma_f32_16x16x32_bf16 v[70:73], v[160:163], v[208:211], v[70:73]
	v_mfma_f32_16x16x32_bf16 v[66:69], v[168:171], v[208:211], v[66:69]
	v_mfma_f32_16x16x32_bf16 v[110:113], v[164:167], v[188:191], v[110:113]
	v_mfma_f32_16x16x32_bf16 v[106:109], v[176:179], v[188:191], v[106:109]
	v_mfma_f32_16x16x32_bf16 v[94:97], v[164:167], v[196:199], v[94:97]
	v_mfma_f32_16x16x32_bf16 v[90:93], v[176:179], v[196:199], v[90:93]
	v_mfma_f32_16x16x32_bf16 v[78:81], v[164:167], v[204:207], v[78:81]
	v_mfma_f32_16x16x32_bf16 v[74:77], v[176:179], v[204:207], v[74:77]
	v_mfma_f32_16x16x32_bf16 v[70:73], v[164:167], v[212:215], v[70:73]
	v_mfma_f32_16x16x32_bf16 v[66:69], v[176:179], v[212:215], v[66:69]
	s_setprio 0
	s_barrier
	s_mov_b32 m0, s71
	v_lshl_add_u64 v[216:217], s[46:47], 0, v[0:1]
	s_add_u32 s28, s46, 0x40000
	ds_read_b128 v[182:185], v141 offset:16384
	ds_read_b128 v[188:191], v141 offset:17408
	ds_read_b128 v[192:195], v141 offset:18432
	ds_read_b128 v[196:199], v141 offset:19456
	ds_read_b128 v[200:203], v141 offset:20480
	ds_read_b128 v[204:207], v141 offset:21504
	ds_read_b128 v[208:211], v141 offset:22528
	ds_read_b128 v[212:215], v141 offset:23552
	global_load_lds_dwordx4 v[216:217], off
	v_lshl_add_u64 v[218:219], s[46:47], 0, v[130:131]
	s_mov_b32 m0, s72
	s_addc_u32 s29, s47, 0
	global_load_lds_dwordx4 v[218:219], off
	v_lshl_add_u64 v[220:221], s[28:29], 0, v[0:1]
	s_mov_b32 m0, s73
	v_lshl_add_u64 v[222:223], s[68:69], 0, v[132:133]
	global_load_lds_dwordx4 v[220:221], off
	v_lshl_add_u64 v[220:221], s[28:29], 0, v[130:131]
	s_mov_b32 m0, s74
	s_nop 0
	global_load_lds_dwordx4 v[220:221], off
	v_lshl_add_u64 v[220:221], s[68:69], 0, v[134:135]
	s_mov_b32 m0, s70
	s_nop 0
	global_load_lds_dwordx4 v[220:221], off
	s_mov_b32 m0, s75
	s_nop 0
	global_load_lds_dwordx4 v[222:223], off
	s_waitcnt vmcnt(8)
	s_waitcnt lgkmcnt(0)
	s_barrier
; #define G_STAGE(bufoff, gbase, voff) do { _Pragma("unroll") for (int _i = 0; _i < 2; ++_i) \
;         __builtin_amdgcn_global_load_lds((const unsigned*)((const char*)(gbase) + (voff)[_i]), (LAS unsigned*)(lds + (bufoff) + ldsw + _i * 8192), 16, 0, 0); } while (0)
; #define G_LDA(dst, b, h) do { _Pragma("unroll") for (int m = 0; m < 4; ++m) _Pragma("unroll") for (int k = 0; k < 2; ++k) dst[m][k] = *(const LAS bf16x8*)(lds + G_SA(b, h) + aoff + m * 2048 + k * 1024); } while (0)
; #define G_LDB(dst, b, h) do { _Pragma("unroll") for (int n = 0; n < 2; ++n) _Pragma("unroll") for (int k = 0; k < 2; ++k) dst[n][k] = *(const LAS bf16x8*)(lds + G_SB(b, h) + boff + n * 2048 + k * 1024); } while (0)
; #define G_MMA(ai, bj, At, Bt_) do { __builtin_amdgcn_s_setprio(1); _Pragma("unroll") for (int m = 0; m < 4; ++m) _Pragma("unroll") for (int n = 0; n < 2; ++n) _Pragma("unroll") for (int k = 0; k < 2; ++k) \
;         acc[ai][bj][m][n] = __builtin_amdgcn_mfma_f32_16x16x32_bf16(Bt_[n][k], At[m][k], acc[ai][bj][m][n], 0, 0, 0); __builtin_amdgcn_s_setprio(0); } while (0)
; #define G_WAIT_V(n) asm volatile("s_waitcnt vmcnt(" #n ")" ::: "memory")
; #define G_WAIT_L(n) asm volatile("s_waitcnt lgkmcnt(" #n ")" ::: "memory")
; #define G_BAR __builtin_amdgcn_s_barrier()
; #define G_SCHED __builtin_amdgcn_sched_barrier(0)
; template <int NSTORE, class TF, class F>
; DEVI void gemm_run(const bf16_t* __restrict__ A, int lda, const bf16_t* __restrict__ Bt, int ldb, int K, bf16_t* shm, TF&& tile, F&& emit) {
;     ...
;             G_LDA(At, 0, 1); G_STAGE(G_SB(0, 0), b2, voffB); G_STAGE(G_SB(0, 1), b2 + hstepB, voffB); G_STAGE(G_SA(0, 0), a2, voffA);
;             G_WAIT_V(8); G_WAIT_L(0); G_BAR; G_MMA(1, 0, At, B0); G_MMA(1, 1, At, B1); G_BAR; G_SCHED;
;             G_LDB(B0, 1, 0); G_LDB(B1, 1, 1); G_SCHED; G_LDA(At, 1, 0); G_STAGE(G_SA(0, 1), a2 + hstepA, voffA);
;             G_WAIT_V(8); G_WAIT_L(0); G_BAR; G_MMA(0, 0, At, B0); G_MMA(0, 1, At, B1); G_BAR; G_SCHED;
	s_setprio 1
	s_waitcnt lgkmcnt(0)
	v_mfma_f32_16x16x32_bf16 v[62:65], v[144:147], v[182:185], v[62:65]
	v_mfma_f32_16x16x32_bf16 v[58:61], v[152:155], v[182:185], v[58:61]
	v_mfma_f32_16x16x32_bf16 v[54:57], v[144:147], v[192:195], v[54:57]
	v_mfma_f32_16x16x32_bf16 v[50:53], v[152:155], v[192:195], v[50:53]
	v_mfma_f32_16x16x32_bf16 v[38:41], v[144:147], v[200:203], v[38:41]
	v_mfma_f32_16x16x32_bf16 v[34:37], v[152:155], v[200:203], v[34:37]
	v_mfma_f32_16x16x32_bf16 v[22:25], v[144:147], v[208:211], v[22:25]
	v_mfma_f32_16x16x32_bf16 v[18:21], v[152:155], v[208:211], v[18:21]
	v_mfma_f32_16x16x32_bf16 v[62:65], v[148:151], v[188:191], v[62:65]
	v_mfma_f32_16x16x32_bf16 v[58:61], v[156:159], v[188:191], v[58:61]
	v_mfma_f32_16x16x32_bf16 v[54:57], v[148:151], v[196:199], v[54:57]
	v_mfma_f32_16x16x32_bf16 v[50:53], v[156:159], v[196:199], v[50:53]
	v_mfma_f32_16x16x32_bf16 v[38:41], v[148:151], v[204:207], v[38:41]
	v_mfma_f32_16x16x32_bf16 v[34:37], v[156:159], v[204:207], v[34:37]
	v_mfma_f32_16x16x32_bf16 v[22:25], v[148:151], v[212:215], v[22:25]
	v_mfma_f32_16x16x32_bf16 v[18:21], v[156:159], v[212:215], v[18:21]
	s_setprio 0
	s_setprio 1
	v_mfma_f32_16x16x32_bf16 v[46:49], v[160:163], v[182:185], v[46:49]
	v_mfma_f32_16x16x32_bf16 v[42:45], v[168:171], v[182:185], v[42:45]
	v_mfma_f32_16x16x32_bf16 v[30:33], v[160:163], v[192:195], v[30:33]
	v_mfma_f32_16x16x32_bf16 v[26:29], v[168:171], v[192:195], v[26:29]
	v_mfma_f32_16x16x32_bf16 v[14:17], v[160:163], v[200:203], v[14:17]
	v_mfma_f32_16x16x32_bf16 v[10:13], v[168:171], v[200:203], v[10:13]
	v_mfma_f32_16x16x32_bf16 v[6:9], v[160:163], v[208:211], v[6:9]
	v_mfma_f32_16x16x32_bf16 v[2:5], v[168:171], v[208:211], v[2:5]
	v_mfma_f32_16x16x32_bf16 v[46:49], v[164:167], v[188:191], v[46:49]
	v_mfma_f32_16x16x32_bf16 v[42:45], v[176:179], v[188:191], v[42:45]
	v_mfma_f32_16x16x32_bf16 v[30:33], v[164:167], v[196:199], v[30:33]
	v_mfma_f32_16x16x32_bf16 v[26:29], v[176:179], v[196:199], v[26:29]
	v_mfma_f32_16x16x32_bf16 v[14:17], v[164:167], v[204:207], v[14:17]
	v_mfma_f32_16x16x32_bf16 v[10:13], v[176:179], v[204:207], v[10:13]
	v_mfma_f32_16x16x32_bf16 v[6:9], v[164:167], v[212:215], v[6:9]
	v_mfma_f32_16x16x32_bf16 v[2:5], v[176:179], v[212:215], v[2:5]
	s_setprio 0
	s_barrier
	v_or_b32_e32 v144, 0x18000, v142
	v_add_u32_e32 v148, 0x18400, v142
	v_add_u32_e32 v152, 0x18800, v142
	v_add_u32_e32 v156, 0x18c00, v142
	v_or_b32_e32 v160, 0x1c000, v142
	v_add_u32_e32 v164, 0x1c400, v142
	v_add_u32_e32 v168, 0x1c800, v142
	v_add_u32_e32 v176, 0x1cc00, v142
	ds_read_b128 v[144:147], v144
	ds_read_b128 v[148:151], v148
	ds_read_b128 v[152:155], v152
	ds_read_b128 v[156:159], v156
	ds_read_b128 v[160:163], v160
	ds_read_b128 v[164:167], v164
	ds_read_b128 v[168:171], v168
	ds_read_b128 v[176:179], v176
	s_add_u32 s28, s68, 0x40000
	s_addc_u32 s29, s69, 0
	s_mov_b32 m0, s76
	v_lshl_add_u64 v[224:225], s[28:29], 0, v[134:135]
	ds_read_b128 v[182:185], v141 offset:32768
	ds_read_b128 v[188:191], v141 offset:33792
	ds_read_b128 v[192:195], v141 offset:34816
	ds_read_b128 v[196:199], v141 offset:35840
	ds_read_b128 v[200:203], v141 offset:36864
	ds_read_b128 v[204:207], v141 offset:37888
	ds_read_b128 v[208:211], v141 offset:38912
	ds_read_b128 v[212:215], v141 offset:39936
	global_load_lds_dwordx4 v[224:225], off
	v_lshl_add_u64 v[224:225], s[28:29], 0, v[132:133]
	s_mov_b32 m0, s77
	s_nop 0
	global_load_lds_dwordx4 v[224:225], off
	s_waitcnt vmcnt(8)
	s_waitcnt lgkmcnt(0)
	s_barrier
	s_setprio 1
	s_waitcnt lgkmcnt(0)
	v_mfma_f32_16x16x32_bf16 v[126:129], v[144:147], v[182:185], v[126:129]
	v_mfma_f32_16x16x32_bf16 v[122:125], v[152:155], v[182:185], v[122:125]
	v_mfma_f32_16x16x32_bf16 v[118:121], v[144:147], v[192:195], v[118:121]
	v_mfma_f32_16x16x32_bf16 v[114:117], v[152:155], v[192:195], v[114:117]
	v_mfma_f32_16x16x32_bf16 v[102:105], v[144:147], v[200:203], v[102:105]
	v_mfma_f32_16x16x32_bf16 v[98:101], v[152:155], v[200:203], v[98:101]
	v_mfma_f32_16x16x32_bf16 v[86:89], v[144:147], v[208:211], v[86:89]
	v_mfma_f32_16x16x32_bf16 v[82:85], v[152:155], v[208:211], v[82:85]
	v_mfma_f32_16x16x32_bf16 v[126:129], v[148:151], v[188:191], v[126:129]
	v_mfma_f32_16x16x32_bf16 v[122:125], v[156:159], v[188:191], v[122:125]
	v_mfma_f32_16x16x32_bf16 v[118:121], v[148:151], v[196:199], v[118:121]
	v_mfma_f32_16x16x32_bf16 v[114:117], v[156:159], v[196:199], v[114:117]
	v_mfma_f32_16x16x32_bf16 v[102:105], v[148:151], v[204:207], v[102:105]
	v_mfma_f32_16x16x32_bf16 v[98:101], v[156:159], v[204:207], v[98:101]
	v_mfma_f32_16x16x32_bf16 v[86:89], v[148:151], v[212:215], v[86:89]
	v_mfma_f32_16x16x32_bf16 v[82:85], v[156:159], v[212:215], v[82:85]
	s_setprio 0
	s_setprio 1
	v_mfma_f32_16x16x32_bf16 v[110:113], v[160:163], v[182:185], v[110:113]
	v_mfma_f32_16x16x32_bf16 v[106:109], v[168:171], v[182:185], v[106:109]
	v_mfma_f32_16x16x32_bf16 v[94:97], v[160:163], v[192:195], v[94:97]
	v_mfma_f32_16x16x32_bf16 v[90:93], v[168:171], v[192:195], v[90:93]
	v_mfma_f32_16x16x32_bf16 v[78:81], v[160:163], v[200:203], v[78:81]
	v_mfma_f32_16x16x32_bf16 v[74:77], v[168:171], v[200:203], v[74:77]
	v_mfma_f32_16x16x32_bf16 v[70:73], v[160:163], v[208:211], v[70:73]
	v_mfma_f32_16x16x32_bf16 v[66:69], v[168:171], v[208:211], v[66:69]
	v_mfma_f32_16x16x32_bf16 v[110:113], v[164:167], v[188:191], v[110:113]
	v_mfma_f32_16x16x32_bf16 v[106:109], v[176:179], v[188:191], v[106:109]
	v_mfma_f32_16x16x32_bf16 v[94:97], v[164:167], v[196:199], v[94:97]
	v_mfma_f32_16x16x32_bf16 v[90:93], v[176:179], v[196:199], v[90:93]
	v_mfma_f32_16x16x32_bf16 v[78:81], v[164:167], v[204:207], v[78:81]
	v_mfma_f32_16x16x32_bf16 v[74:77], v[176:179], v[204:207], v[74:77]
	v_mfma_f32_16x16x32_bf16 v[70:73], v[164:167], v[212:215], v[70:73]
	v_mfma_f32_16x16x32_bf16 v[66:69], v[176:179], v[212:215], v[66:69]
	s_setprio 0
	s_barrier
; #define G_STAGE(bufoff, gbase, voff) do { _Pragma("unroll") for (int _i = 0; _i < 2; ++_i) \
;         __builtin_amdgcn_global_load_lds((const unsigned*)((const char*)(gbase) + (voff)[_i]), (LAS unsigned*)(lds + (bufoff) + ldsw + _i * 8192), 16, 0, 0); } while (0)
; #define G_LDA(dst, b, h) do { _Pragma("unroll") for (int m = 0; m < 4; ++m) _Pragma("unroll") for (int k = 0; k < 2; ++k) dst[m][k] = *(const LAS bf16x8*)(lds + G_SA(b, h) + aoff + m * 2048 + k * 1024); } while (0)
; #define G_LDB(dst, b, h) do { _Pragma("unroll") for (int n = 0; n < 2; ++n) _Pragma("unroll") for (int k = 0; k < 2; ++k) dst[n][k] = *(const LAS bf16x8*)(lds + G_SB(b, h) + boff + n * 2048 + k * 1024); } while (0)
; #define G_WAIT_V(n) asm volatile("s_waitcnt vmcnt(" #n ")" ::: "memory")
; #define G_WAIT_L(n) asm volatile("s_waitcnt lgkmcnt(" #n ")" ::: "memory")
; #define G_BAR __builtin_amdgcn_s_barrier()
; template <int NSTORE, class TF, class F>
; DEVI void gemm_run(const bf16_t* __restrict__ A, int lda, const bf16_t* __restrict__ Bt, int ldb, int K, bf16_t* shm, TF&& tile, F&& emit) {
;     ...
;         for (int t = 0; t < nt; t += 2) {
;             const bool last = (t == nt - 2);
;             const char* a1 = cA + (size_t)(t + 1) * kstep;
;             const char* a2 = last ? nA : cA + (size_t)(t + 2) * kstep; const char* b2 = last ? nB : cB + (size_t)(t + 2) * kstep;
;             const char* a3 = a2 + kstep; const char* b3 = b2 + kstep;
;             G_LDB(B0, 0, 0); G_LDB(B1, 0, 1); G_SCHED; G_LDA(At, 0, 0); G_STAGE(G_SA(1, 1), a1 + hstepA, voffA);
;             G_WAIT_V(8); G_WAIT_L(0); G_BAR; G_MMA(0, 0, At, B0); G_MMA(0, 1, At, B1); G_BAR; G_SCHED;
;             G_LDA(At, 0, 1); G_STAGE(G_SB(0, 0), b2, voffB); G_STAGE(G_SB(0, 1), b2 + hstepB, voffB); G_STAGE(G_SA(0, 0), a2, voffA);
;             G_WAIT_V(8); G_WAIT_L(0); G_BAR; G_MMA(1, 0, At, B0); G_MMA(1, 1, At, B1); G_BAR; G_SCHED;
;             G_LDB(B0, 1, 0); G_LDB(B1, 1, 1); G_SCHED; G_LDA(At, 1, 0); G_STAGE(G_SA(0, 1), a2 + hstepA, voffA);
;             G_WAIT_V(8); G_WAIT_L(0); G_BAR; G_MMA(0, 0, At, B0); G_MMA(0, 1, At, B1); G_BAR; G_SCHED;
;             G_LDA(At, 1, 1); G_STAGE(G_SB(1, 0), b3, voffB); G_STAGE(G_SB(1, 1), b3 + hstepB, voffB); G_STAGE(G_SA(1, 0), a3, voffA);
;             G_WAIT_V(8); G_WAIT_L(0); G_BAR; G_MMA(1, 0, At, B0); G_MMA(1, 1, At, B1); G_BAR; G_SCHED;
	s_mov_b32 m0, s78
	v_lshl_add_u64 v[216:217], v[216:217], 0, s[30:31]
	s_add_u32 s28, s46, 0x40080
	ds_read_b128 v[182:185], v141 offset:49152
	ds_read_b128 v[188:191], v141 offset:50176
	ds_read_b128 v[192:195], v141 offset:51200
	ds_read_b128 v[196:199], v141 offset:52224
	ds_read_b128 v[200:203], v141 offset:53248
	ds_read_b128 v[204:207], v141 offset:54272
	ds_read_b128 v[208:211], v141 offset:55296
	ds_read_b128 v[212:215], v141 offset:56320
	global_load_lds_dwordx4 v[216:217], off
	v_lshl_add_u64 v[216:217], v[218:219], 0, s[30:31]
	s_mov_b32 m0, s26
	s_addc_u32 s29, s47, 0
	global_load_lds_dwordx4 v[216:217], off
	v_lshl_add_u64 v[216:217], s[28:29], 0, v[0:1]
	s_mov_b32 m0, s83
	s_nop 0
	global_load_lds_dwordx4 v[216:217], off
	v_lshl_add_u64 v[216:217], s[28:29], 0, v[130:131]
	s_mov_b32 m0, s94
	s_nop 0
	global_load_lds_dwordx4 v[216:217], off
	v_lshl_add_u64 v[216:217], v[220:221], 0, s[30:31]
	s_mov_b32 m0, s27
	s_nop 0
	global_load_lds_dwordx4 v[216:217], off
	v_lshl_add_u64 v[216:217], v[222:223], 0, s[30:31]
	s_mov_b32 m0, s79
	s_nop 0
	global_load_lds_dwordx4 v[216:217], off
	s_waitcnt vmcnt(8)
	s_waitcnt lgkmcnt(0)
	s_barrier
	s_setprio 1
	s_waitcnt lgkmcnt(0)
	v_mfma_f32_16x16x32_bf16 v[62:65], v[144:147], v[182:185], v[62:65]
	v_mfma_f32_16x16x32_bf16 v[58:61], v[152:155], v[182:185], v[58:61]
	v_mfma_f32_16x16x32_bf16 v[54:57], v[144:147], v[192:195], v[54:57]
	v_mfma_f32_16x16x32_bf16 v[50:53], v[152:155], v[192:195], v[50:53]
	v_mfma_f32_16x16x32_bf16 v[38:41], v[144:147], v[200:203], v[38:41]
	v_mfma_f32_16x16x32_bf16 v[34:37], v[152:155], v[200:203], v[34:37]
	v_mfma_f32_16x16x32_bf16 v[22:25], v[144:147], v[208:211], v[22:25]
	v_mfma_f32_16x16x32_bf16 v[18:21], v[152:155], v[208:211], v[18:21]
	v_mfma_f32_16x16x32_bf16 v[62:65], v[148:151], v[188:191], v[62:65]
	v_mfma_f32_16x16x32_bf16 v[58:61], v[156:159], v[188:191], v[58:61]
	v_mfma_f32_16x16x32_bf16 v[54:57], v[148:151], v[196:199], v[54:57]
	v_mfma_f32_16x16x32_bf16 v[50:53], v[156:159], v[196:199], v[50:53]
	v_mfma_f32_16x16x32_bf16 v[38:41], v[148:151], v[204:207], v[38:41]
	v_mfma_f32_16x16x32_bf16 v[34:37], v[156:159], v[204:207], v[34:37]
	v_mfma_f32_16x16x32_bf16 v[22:25], v[148:151], v[212:215], v[22:25]
	v_mfma_f32_16x16x32_bf16 v[18:21], v[156:159], v[212:215], v[18:21]
	s_setprio 0
	s_setprio 1
	v_mfma_f32_16x16x32_bf16 v[46:49], v[160:163], v[182:185], v[46:49]
	v_mfma_f32_16x16x32_bf16 v[42:45], v[168:171], v[182:185], v[42:45]
	v_mfma_f32_16x16x32_bf16 v[30:33], v[160:163], v[192:195], v[30:33]
	v_mfma_f32_16x16x32_bf16 v[26:29], v[168:171], v[192:195], v[26:29]
	v_mfma_f32_16x16x32_bf16 v[14:17], v[160:163], v[200:203], v[14:17]
	s_add_i32 s82, s82, 2
	v_mfma_f32_16x16x32_bf16 v[10:13], v[168:171], v[200:203], v[10:13]
	v_mfma_f32_16x16x32_bf16 v[6:9], v[160:163], v[208:211], v[6:9]
	s_add_u32 s44, s44, 0x100
	v_mfma_f32_16x16x32_bf16 v[2:5], v[168:171], v[208:211], v[2:5]
	v_mfma_f32_16x16x32_bf16 v[46:49], v[164:167], v[188:191], v[46:49]
	s_addc_u32 s45, s45, 0
	v_mfma_f32_16x16x32_bf16 v[42:45], v[176:179], v[188:191], v[42:45]
	v_mfma_f32_16x16x32_bf16 v[30:33], v[164:167], v[196:199], v[30:33]
	s_add_u32 s33, s33, 0x100
	v_mfma_f32_16x16x32_bf16 v[26:29], v[176:179], v[196:199], v[26:29]
	v_mfma_f32_16x16x32_bf16 v[14:17], v[164:167], v[204:207], v[14:17]
	s_addc_u32 s3, s3, 0
	v_mfma_f32_16x16x32_bf16 v[10:13], v[176:179], v[204:207], v[10:13]
	v_mfma_f32_16x16x32_bf16 v[6:9], v[164:167], v[212:215], v[6:9]
	s_cmp_gt_u32 s82, 13
	v_mfma_f32_16x16x32_bf16 v[2:5], v[176:179], v[212:215], v[2:5]
	s_setprio 0
	s_barrier
	s_cbranch_scc0 .LBB0_545
	s_and_b64 vcc, exec, s[14:15]
	s_cbranch_vccz .LBB0_548
	s_barrier

; #define G_STAGE(bufoff, gbase, voff) do { _Pragma("unroll") for (int _i = 0; _i < 2; ++_i) \
;         __builtin_amdgcn_global_load_lds((const unsigned*)((const char*)(gbase) + (voff)[_i]), (LAS unsigned*)(lds + (bufoff) + ldsw + _i * 8192), 16, 0, 0); } while (0)
; #define G_LDA(dst, b, h) do { _Pragma("unroll") for (int m = 0; m < 4; ++m) _Pragma("unroll") for (int k = 0; k < 2; ++k) dst[m][k] = *(const LAS bf16x8*)(lds + G_SA(b, h) + aoff + m * 2048 + k * 1024); } while (0)
; #define G_LDB(dst, b, h) do { _Pragma("unroll") for (int n = 0; n < 2; ++n) _Pragma("unroll") for (int k = 0; k < 2; ++k) dst[n][k] = *(const LAS bf16x8*)(lds + G_SB(b, h) + boff + n * 2048 + k * 1024); } while (0)
; #define G_MMA(ai, bj, At, Bt_) do { __builtin_amdgcn_s_setprio(1); _Pragma("unroll") for (int m = 0; m < 4; ++m) _Pragma("unroll") for (int n = 0; n < 2; ++n) _Pragma("unroll") for (int k = 0; k < 2; ++k) \
;         acc[ai][bj][m][n] = __builtin_amdgcn_mfma_f32_16x16x32_bf16(Bt_[n][k], At[m][k], acc[ai][bj][m][n], 0, 0, 0); __builtin_amdgcn_s_setprio(0); } while (0)
; #define G_WAIT_V(n) asm volatile("s_waitcnt vmcnt(" #n ")" ::: "memory")
; #define G_WAIT_L(n) asm volatile("s_waitcnt lgkmcnt(" #n ")" ::: "memory")
; #define G_BAR __builtin_amdgcn_s_barrier()
; template <int NSTORE, class TF, class F>
; DEVI void gemm_run(const bf16_t* __restrict__ A, int lda, const bf16_t* __restrict__ Bt, int ldb, int K, bf16_t* shm, TF&& tile, F&& emit) {
;     ...
;         const bool has_next = tile(ui + 1, nrow, ncol);
;         const char* nA = has_next ? (const char*)A + (size_t)nrow * lda * 2 : cA; const char* nB = has_next ? (const char*)Bt + (size_t)ncol * ldb * 2 : cB;
;         for (int t = 0; t < nt; t += 2) {
;             const bool last = (t == nt - 2);
;             const char* a1 = cA + (size_t)(t + 1) * kstep;
;             const char* a2 = last ? nA : cA + (size_t)(t + 2) * kstep; const char* b2 = last ? nB : cB + (size_t)(t + 2) * kstep;
;             const char* a3 = a2 + kstep; const char* b3 = b2 + kstep;
;             G_LDB(B0, 0, 0); G_LDB(B1, 0, 1); G_SCHED; G_LDA(At, 0, 0); G_STAGE(G_SA(1, 1), a1 + hstepA, voffA);
;             G_WAIT_V(8); G_WAIT_L(0); G_BAR; G_MMA(0, 0, At, B0); G_MMA(0, 1, At, B1); G_BAR; G_SCHED;
;             G_LDA(At, 0, 1); G_STAGE(G_SB(0, 0), b2, voffB); G_STAGE(G_SB(0, 1), b2 + hstepB, voffB); G_STAGE(G_SA(0, 0), a2, voffA);
.LBB0_803:
	v_or_b32_e32 v144, 0x10000, v142
	v_add_u32_e32 v148, 0x10400, v142
	ds_read_b128 v[144:147], v144
	ds_read_b128 v[150:153], v148
	v_add_u32_e32 v148, 0x10800, v142
	v_add_u32_e32 v149, 0x10c00, v142
	ds_read_b128 v[154:157], v148
	ds_read_b128 v[158:161], v149
	v_or_b32_e32 v148, 0x14000, v142
	v_add_u32_e32 v149, 0x14400, v142
	ds_read_b128 v[162:165], v148
	ds_read_b128 v[188:191], v149
	v_add_u32_e32 v148, 0x14800, v142
	v_add_u32_e32 v149, 0x14c00, v142
	ds_read_b128 v[192:195], v148
	ds_read_b128 v[196:199], v149
	s_add_u32 s28, s40, 0xfffc0080
	s_addc_u32 s29, s41, -1
	s_cmp_eq_u32 s3, 12
	s_cselect_b32 s45, s9, s29
	s_cselect_b32 s44, s79, s28
	s_cselect_b32 s43, s15, s33
	s_cselect_b32 s42, s83, s94
	v_lshl_add_u64 v[148:149], s[40:41], 0, v[136:137]
	s_add_i32 m0, s46, 0xc000
	ds_read_b128 v[200:203], v141
	ds_read_b128 v[204:207], v141 offset:1024
	ds_read_b128 v[208:211], v141 offset:2048
	ds_read_b128 v[212:215], v141 offset:3072
	ds_read_b128 v[216:219], v141 offset:4096
	ds_read_b128 v[220:223], v141 offset:5120
	ds_read_b128 v[224:227], v141 offset:6144
	ds_read_b128 v[228:231], v141 offset:7168
	global_load_lds_dwordx4 v[148:149], off
	v_lshl_add_u64 v[148:149], s[40:41], 0, v[138:139]
	s_add_i32 m0, s46, 0xe000
	s_nop 0
	global_load_lds_dwordx4 v[148:149], off
	s_waitcnt vmcnt(8)
	s_waitcnt lgkmcnt(0)
	s_barrier
	s_setprio 1
	s_waitcnt lgkmcnt(0)
	v_mfma_f32_16x16x32_bf16 v[126:129], v[144:147], v[200:203], v[126:129]
	v_mfma_f32_16x16x32_bf16 v[122:125], v[154:157], v[200:203], v[122:125]
	v_mfma_f32_16x16x32_bf16 v[118:121], v[144:147], v[208:211], v[118:121]
	v_mfma_f32_16x16x32_bf16 v[114:117], v[154:157], v[208:211], v[114:117]
	v_mfma_f32_16x16x32_bf16 v[102:105], v[144:147], v[216:219], v[102:105]
	v_mfma_f32_16x16x32_bf16 v[98:101], v[154:157], v[216:219], v[98:101]
	v_mfma_f32_16x16x32_bf16 v[86:89], v[144:147], v[224:227], v[86:89]
	v_mfma_f32_16x16x32_bf16 v[82:85], v[154:157], v[224:227], v[82:85]
	v_mfma_f32_16x16x32_bf16 v[126:129], v[150:153], v[204:207], v[126:129]
	v_mfma_f32_16x16x32_bf16 v[122:125], v[158:161], v[204:207], v[122:125]
	v_mfma_f32_16x16x32_bf16 v[118:121], v[150:153], v[212:215], v[118:121]
	v_mfma_f32_16x16x32_bf16 v[114:117], v[158:161], v[212:215], v[114:117]
	v_mfma_f32_16x16x32_bf16 v[102:105], v[150:153], v[220:223], v[102:105]
	v_mfma_f32_16x16x32_bf16 v[98:101], v[158:161], v[220:223], v[98:101]
	v_mfma_f32_16x16x32_bf16 v[86:89], v[150:153], v[228:231], v[86:89]
	v_mfma_f32_16x16x32_bf16 v[82:85], v[158:161], v[228:231], v[82:85]
	s_setprio 0
	s_setprio 1
	v_mfma_f32_16x16x32_bf16 v[110:113], v[162:165], v[200:203], v[110:113]
	v_mfma_f32_16x16x32_bf16 v[106:109], v[192:195], v[200:203], v[106:109]
	v_mfma_f32_16x16x32_bf16 v[94:97], v[162:165], v[208:211], v[94:97]
	v_mfma_f32_16x16x32_bf16 v[90:93], v[192:195], v[208:211], v[90:93]
	v_mfma_f32_16x16x32_bf16 v[78:81], v[162:165], v[216:219], v[78:81]
	v_mfma_f32_16x16x32_bf16 v[74:77], v[192:195], v[216:219], v[74:77]
	v_mfma_f32_16x16x32_bf16 v[70:73], v[162:165], v[224:227], v[70:73]
	v_mfma_f32_16x16x32_bf16 v[66:69], v[192:195], v[224:227], v[66:69]
	v_mfma_f32_16x16x32_bf16 v[110:113], v[188:191], v[204:207], v[110:113]
	v_mfma_f32_16x16x32_bf16 v[106:109], v[196:199], v[204:207], v[106:109]
	v_mfma_f32_16x16x32_bf16 v[94:97], v[188:191], v[212:215], v[94:97]
	v_mfma_f32_16x16x32_bf16 v[90:93], v[196:199], v[212:215], v[90:93]
	v_mfma_f32_16x16x32_bf16 v[78:81], v[188:191], v[220:223], v[78:81]
	v_mfma_f32_16x16x32_bf16 v[74:77], v[196:199], v[220:223], v[74:77]
	v_mfma_f32_16x16x32_bf16 v[70:73], v[188:191], v[228:231], v[70:73]
	v_mfma_f32_16x16x32_bf16 v[66:69], v[196:199], v[228:231], v[66:69]
	s_setprio 0
	s_barrier
	s_mov_b32 m0, s47
	v_lshl_add_u64 v[148:149], s[42:43], 0, v[0:1]
	s_add_u32 vcc_lo, s42, 0x40000
	ds_read_b128 v[200:203], v141 offset:16384
	ds_read_b128 v[204:207], v141 offset:17408
	ds_read_b128 v[208:211], v141 offset:18432
	ds_read_b128 v[212:215], v141 offset:19456
	ds_read_b128 v[216:219], v141 offset:20480
	ds_read_b128 v[220:223], v141 offset:21504
	ds_read_b128 v[224:227], v141 offset:22528
	ds_read_b128 v[228:231], v141 offset:23552
	global_load_lds_dwordx4 v[148:149], off
	v_lshl_add_u64 v[166:167], s[42:43], 0, v[130:131]
	s_mov_b32 m0, s68
	s_addc_u32 vcc_hi, s43, 0
	global_load_lds_dwordx4 v[166:167], off
	v_lshl_add_u64 v[168:169], vcc, 0, v[0:1]
	s_mov_b32 m0, s69
	v_lshl_add_u64 v[170:171], s[44:45], 0, v[132:133]
	global_load_lds_dwordx4 v[168:169], off
	v_lshl_add_u64 v[168:169], vcc, 0, v[130:131]
	s_mov_b32 m0, s70
	s_nop 0
	global_load_lds_dwordx4 v[168:169], off
	v_lshl_add_u64 v[168:169], s[44:45], 0, v[134:135]
	s_mov_b32 m0, s46
	s_nop 0
	global_load_lds_dwordx4 v[168:169], off
	s_mov_b32 m0, s71
	s_nop 0
	global_load_lds_dwordx4 v[170:171], off
	s_waitcnt vmcnt(8)
	s_waitcnt lgkmcnt(0)
	s_barrier
; #define G_STAGE(bufoff, gbase, voff) do { _Pragma("unroll") for (int _i = 0; _i < 2; ++_i) \
;         __builtin_amdgcn_global_load_lds((const unsigned*)((const char*)(gbase) + (voff)[_i]), (LAS unsigned*)(lds + (bufoff) + ldsw + _i * 8192), 16, 0, 0); } while (0)
; #define G_LDA(dst, b, h) do { _Pragma("unroll") for (int m = 0; m < 4; ++m) _Pragma("unroll") for (int k = 0; k < 2; ++k) dst[m][k] = *(const LAS bf16x8*)(lds + G_SA(b, h) + aoff + m * 2048 + k * 1024); } while (0)
; #define G_LDB(dst, b, h) do { _Pragma("unroll") for (int n = 0; n < 2; ++n) _Pragma("unroll") for (int k = 0; k < 2; ++k) dst[n][k] = *(const LAS bf16x8*)(lds + G_SB(b, h) + boff + n * 2048 + k * 1024); } while (0)
; #define G_MMA(ai, bj, At, Bt_) do { __builtin_amdgcn_s_setprio(1); _Pragma("unroll") for (int m = 0; m < 4; ++m) _Pragma("unroll") for (int n = 0; n < 2; ++n) _Pragma("unroll") for (int k = 0; k < 2; ++k) \
;         acc[ai][bj][m][n] = __builtin_amdgcn_mfma_f32_16x16x32_bf16(Bt_[n][k], At[m][k], acc[ai][bj][m][n], 0, 0, 0); __builtin_amdgcn_s_setprio(0); } while (0)
; #define G_WAIT_V(n) asm volatile("s_waitcnt vmcnt(" #n ")" ::: "memory")
; #define G_WAIT_L(n) asm volatile("s_waitcnt lgkmcnt(" #n ")" ::: "memory")
; #define G_BAR __builtin_amdgcn_s_barrier()
; #define G_SCHED __builtin_amdgcn_sched_barrier(0)
; template <int NSTORE, class TF, class F>
; DEVI void gemm_run(const bf16_t* __restrict__ A, int lda, const bf16_t* __restrict__ Bt, int ldb, int K, bf16_t* shm, TF&& tile, F&& emit) {
;     ...
;             G_LDA(At, 0, 1); G_STAGE(G_SB(0, 0), b2, voffB); G_STAGE(G_SB(0, 1), b2 + hstepB, voffB); G_STAGE(G_SA(0, 0), a2, voffA);
;             G_WAIT_V(8); G_WAIT_L(0); G_BAR; G_MMA(1, 0, At, B0); G_MMA(1, 1, At, B1); G_BAR; G_SCHED;
;             G_LDB(B0, 1, 0); G_LDB(B1, 1, 1); G_SCHED; G_LDA(At, 1, 0); G_STAGE(G_SA(0, 1), a2 + hstepA, voffA);
;             G_WAIT_V(8); G_WAIT_L(0); G_BAR; G_MMA(0, 0, At, B0); G_MMA(0, 1, At, B1); G_BAR; G_SCHED;
	s_setprio 1
	s_waitcnt lgkmcnt(0)
	v_mfma_f32_16x16x32_bf16 v[62:65], v[144:147], v[200:203], v[62:65]
	v_mfma_f32_16x16x32_bf16 v[58:61], v[154:157], v[200:203], v[58:61]
	v_mfma_f32_16x16x32_bf16 v[54:57], v[144:147], v[208:211], v[54:57]
	v_mfma_f32_16x16x32_bf16 v[50:53], v[154:157], v[208:211], v[50:53]
	v_mfma_f32_16x16x32_bf16 v[38:41], v[144:147], v[216:219], v[38:41]
	v_mfma_f32_16x16x32_bf16 v[34:37], v[154:157], v[216:219], v[34:37]
	v_mfma_f32_16x16x32_bf16 v[22:25], v[144:147], v[224:227], v[22:25]
	v_mfma_f32_16x16x32_bf16 v[18:21], v[154:157], v[224:227], v[18:21]
	v_mfma_f32_16x16x32_bf16 v[62:65], v[150:153], v[204:207], v[62:65]
	v_mfma_f32_16x16x32_bf16 v[58:61], v[158:161], v[204:207], v[58:61]
	v_mfma_f32_16x16x32_bf16 v[54:57], v[150:153], v[212:215], v[54:57]
	v_mfma_f32_16x16x32_bf16 v[50:53], v[158:161], v[212:215], v[50:53]
	v_mfma_f32_16x16x32_bf16 v[38:41], v[150:153], v[220:223], v[38:41]
	v_mfma_f32_16x16x32_bf16 v[34:37], v[158:161], v[220:223], v[34:37]
	v_mfma_f32_16x16x32_bf16 v[22:25], v[150:153], v[228:231], v[22:25]
	v_mfma_f32_16x16x32_bf16 v[18:21], v[158:161], v[228:231], v[18:21]
	s_setprio 0
	s_setprio 1
	v_mfma_f32_16x16x32_bf16 v[46:49], v[162:165], v[200:203], v[46:49]
	v_mfma_f32_16x16x32_bf16 v[42:45], v[192:195], v[200:203], v[42:45]
	v_mfma_f32_16x16x32_bf16 v[30:33], v[162:165], v[208:211], v[30:33]
	v_mfma_f32_16x16x32_bf16 v[26:29], v[192:195], v[208:211], v[26:29]
	v_mfma_f32_16x16x32_bf16 v[14:17], v[162:165], v[216:219], v[14:17]
	v_mfma_f32_16x16x32_bf16 v[10:13], v[192:195], v[216:219], v[10:13]
	v_mfma_f32_16x16x32_bf16 v[6:9], v[162:165], v[224:227], v[6:9]
	v_mfma_f32_16x16x32_bf16 v[2:5], v[192:195], v[224:227], v[2:5]
	v_mfma_f32_16x16x32_bf16 v[46:49], v[188:191], v[204:207], v[46:49]
	v_mfma_f32_16x16x32_bf16 v[42:45], v[196:199], v[204:207], v[42:45]
	v_mfma_f32_16x16x32_bf16 v[30:33], v[188:191], v[212:215], v[30:33]
	v_mfma_f32_16x16x32_bf16 v[26:29], v[196:199], v[212:215], v[26:29]
	v_mfma_f32_16x16x32_bf16 v[14:17], v[188:191], v[220:223], v[14:17]
	v_mfma_f32_16x16x32_bf16 v[10:13], v[196:199], v[220:223], v[10:13]
	v_mfma_f32_16x16x32_bf16 v[6:9], v[188:191], v[228:231], v[6:9]
	v_mfma_f32_16x16x32_bf16 v[2:5], v[196:199], v[228:231], v[2:5]
	s_setprio 0
	s_barrier
	v_or_b32_e32 v144, 0x18000, v142
	v_add_u32_e32 v150, 0x18400, v142
	v_add_u32_e32 v154, 0x18800, v142
	v_add_u32_e32 v158, 0x18c00, v142
	v_or_b32_e32 v162, 0x1c000, v142
	v_add_u32_e32 v176, 0x1c400, v142
	ds_read_b128 v[144:147], v144
	ds_read_b128 v[150:153], v150
	ds_read_b128 v[154:157], v154
	ds_read_b128 v[158:161], v158
	ds_read_b128 v[162:165], v162
	ds_read_b128 v[188:191], v176
	v_add_u32_e32 v176, 0x1c800, v142
	v_add_u32_e32 v177, 0x1cc00, v142
	ds_read_b128 v[192:195], v176
	ds_read_b128 v[196:199], v177
	s_add_u32 s44, s44, 0x40000
	s_addc_u32 s45, s45, 0
	s_mov_b32 m0, s72
	v_lshl_add_u64 v[176:177], s[44:45], 0, v[134:135]
	ds_read_b128 v[200:203], v141 offset:32768
	ds_read_b128 v[204:207], v141 offset:33792
	ds_read_b128 v[208:211], v141 offset:34816
	ds_read_b128 v[212:215], v141 offset:35840
	ds_read_b128 v[216:219], v141 offset:36864
	ds_read_b128 v[220:223], v141 offset:37888
	ds_read_b128 v[224:227], v141 offset:38912
	ds_read_b128 v[228:231], v141 offset:39936
	global_load_lds_dwordx4 v[176:177], off
	v_lshl_add_u64 v[176:177], s[44:45], 0, v[132:133]
	s_mov_b32 m0, s73
	s_nop 0
	global_load_lds_dwordx4 v[176:177], off
	s_waitcnt vmcnt(8)
	s_waitcnt lgkmcnt(0)
	s_barrier
	s_setprio 1
	s_waitcnt lgkmcnt(0)
	v_mfma_f32_16x16x32_bf16 v[126:129], v[144:147], v[200:203], v[126:129]
	v_mfma_f32_16x16x32_bf16 v[122:125], v[154:157], v[200:203], v[122:125]
	v_mfma_f32_16x16x32_bf16 v[118:121], v[144:147], v[208:211], v[118:121]
	v_mfma_f32_16x16x32_bf16 v[114:117], v[154:157], v[208:211], v[114:117]
	v_mfma_f32_16x16x32_bf16 v[102:105], v[144:147], v[216:219], v[102:105]
	v_mfma_f32_16x16x32_bf16 v[98:101], v[154:157], v[216:219], v[98:101]
	v_mfma_f32_16x16x32_bf16 v[86:89], v[144:147], v[224:227], v[86:89]
	v_mfma_f32_16x16x32_bf16 v[82:85], v[154:157], v[224:227], v[82:85]
	v_mfma_f32_16x16x32_bf16 v[126:129], v[150:153], v[204:207], v[126:129]
	v_mfma_f32_16x16x32_bf16 v[122:125], v[158:161], v[204:207], v[122:125]
	v_mfma_f32_16x16x32_bf16 v[118:121], v[150:153], v[212:215], v[118:121]
	v_mfma_f32_16x16x32_bf16 v[114:117], v[158:161], v[212:215], v[114:117]
	v_mfma_f32_16x16x32_bf16 v[102:105], v[150:153], v[220:223], v[102:105]
	v_mfma_f32_16x16x32_bf16 v[98:101], v[158:161], v[220:223], v[98:101]
	v_mfma_f32_16x16x32_bf16 v[86:89], v[150:153], v[228:231], v[86:89]
	v_mfma_f32_16x16x32_bf16 v[82:85], v[158:161], v[228:231], v[82:85]
	s_setprio 0
	s_setprio 1
	v_mfma_f32_16x16x32_bf16 v[110:113], v[162:165], v[200:203], v[110:113]
	v_mfma_f32_16x16x32_bf16 v[106:109], v[192:195], v[200:203], v[106:109]
	v_mfma_f32_16x16x32_bf16 v[94:97], v[162:165], v[208:211], v[94:97]
	v_mfma_f32_16x16x32_bf16 v[90:93], v[192:195], v[208:211], v[90:93]
	v_mfma_f32_16x16x32_bf16 v[78:81], v[162:165], v[216:219], v[78:81]
	v_mfma_f32_16x16x32_bf16 v[74:77], v[192:195], v[216:219], v[74:77]
	v_mfma_f32_16x16x32_bf16 v[70:73], v[162:165], v[224:227], v[70:73]
	v_mfma_f32_16x16x32_bf16 v[66:69], v[192:195], v[224:227], v[66:69]
	v_mfma_f32_16x16x32_bf16 v[110:113], v[188:191], v[204:207], v[110:113]
	v_mfma_f32_16x16x32_bf16 v[106:109], v[196:199], v[204:207], v[106:109]
	v_mfma_f32_16x16x32_bf16 v[94:97], v[188:191], v[212:215], v[94:97]
	v_mfma_f32_16x16x32_bf16 v[90:93], v[196:199], v[212:215], v[90:93]
	v_mfma_f32_16x16x32_bf16 v[78:81], v[188:191], v[220:223], v[78:81]
	v_mfma_f32_16x16x32_bf16 v[74:77], v[196:199], v[220:223], v[74:77]
	v_mfma_f32_16x16x32_bf16 v[70:73], v[188:191], v[228:231], v[70:73]
	v_mfma_f32_16x16x32_bf16 v[66:69], v[196:199], v[228:231], v[66:69]
	s_setprio 0
	s_barrier
; #define G_STAGE(bufoff, gbase, voff) do { _Pragma("unroll") for (int _i = 0; _i < 2; ++_i) \
;         __builtin_amdgcn_global_load_lds((const unsigned*)((const char*)(gbase) + (voff)[_i]), (LAS unsigned*)(lds + (bufoff) + ldsw + _i * 8192), 16, 0, 0); } while (0)
; #define G_LDA(dst, b, h) do { _Pragma("unroll") for (int m = 0; m < 4; ++m) _Pragma("unroll") for (int k = 0; k < 2; ++k) dst[m][k] = *(const LAS bf16x8*)(lds + G_SA(b, h) + aoff + m * 2048 + k * 1024); } while (0)
; #define G_LDB(dst, b, h) do { _Pragma("unroll") for (int n = 0; n < 2; ++n) _Pragma("unroll") for (int k = 0; k < 2; ++k) dst[n][k] = *(const LAS bf16x8*)(lds + G_SB(b, h) + boff + n * 2048 + k * 1024); } while (0)
; #define G_WAIT_V(n) asm volatile("s_waitcnt vmcnt(" #n ")" ::: "memory")
; #define G_WAIT_L(n) asm volatile("s_waitcnt lgkmcnt(" #n ")" ::: "memory")
; #define G_BAR __builtin_amdgcn_s_barrier()
; template <int NSTORE, class TF, class F>
; DEVI void gemm_run(const bf16_t* __restrict__ A, int lda, const bf16_t* __restrict__ Bt, int ldb, int K, bf16_t* shm, TF&& tile, F&& emit) {
;     ...
;         for (int t = 0; t < nt; t += 2) {
;             const bool last = (t == nt - 2);
;             const char* a1 = cA + (size_t)(t + 1) * kstep;
;             const char* a2 = last ? nA : cA + (size_t)(t + 2) * kstep; const char* b2 = last ? nB : cB + (size_t)(t + 2) * kstep;
;             const char* a3 = a2 + kstep; const char* b3 = b2 + kstep;
;             G_LDB(B0, 0, 0); G_LDB(B1, 0, 1); G_SCHED; G_LDA(At, 0, 0); G_STAGE(G_SA(1, 1), a1 + hstepA, voffA);
;             G_WAIT_V(8); G_WAIT_L(0); G_BAR; G_MMA(0, 0, At, B0); G_MMA(0, 1, At, B1); G_BAR; G_SCHED;
;             G_LDA(At, 0, 1); G_STAGE(G_SB(0, 0), b2, voffB); G_STAGE(G_SB(0, 1), b2 + hstepB, voffB); G_STAGE(G_SA(0, 0), a2, voffA);
;             G_WAIT_V(8); G_WAIT_L(0); G_BAR; G_MMA(1, 0, At, B0); G_MMA(1, 1, At, B1); G_BAR; G_SCHED;
;             G_LDB(B0, 1, 0); G_LDB(B1, 1, 1); G_SCHED; G_LDA(At, 1, 0); G_STAGE(G_SA(0, 1), a2 + hstepA, voffA);
;             G_WAIT_V(8); G_WAIT_L(0); G_BAR; G_MMA(0, 0, At, B0); G_MMA(0, 1, At, B1); G_BAR; G_SCHED;
;             G_LDA(At, 1, 1); G_STAGE(G_SB(1, 0), b3, voffB); G_STAGE(G_SB(1, 1), b3 + hstepB, voffB); G_STAGE(G_SA(1, 0), a3, voffA);
;             G_WAIT_V(8); G_WAIT_L(0); G_BAR; G_MMA(1, 0, At, B0); G_MMA(1, 1, At, B1); G_BAR; G_SCHED;
	s_mov_b32 m0, s26
	v_lshl_add_u64 v[148:149], v[148:149], 0, s[30:31]
	s_add_u32 s42, s42, 0x40080
	ds_read_b128 v[200:203], v141 offset:49152
	ds_read_b128 v[204:207], v141 offset:50176
	ds_read_b128 v[208:211], v141 offset:51200
	ds_read_b128 v[212:215], v141 offset:52224
	ds_read_b128 v[216:219], v141 offset:53248
	ds_read_b128 v[220:223], v141 offset:54272
	ds_read_b128 v[224:227], v141 offset:55296
	ds_read_b128 v[228:231], v141 offset:56320
	global_load_lds_dwordx4 v[148:149], off
	v_lshl_add_u64 v[148:149], v[166:167], 0, s[30:31]
	s_mov_b32 m0, s27
	s_addc_u32 s43, s43, 0
	global_load_lds_dwordx4 v[148:149], off
	v_lshl_add_u64 v[148:149], s[42:43], 0, v[0:1]
	s_mov_b32 m0, s76
	s_nop 0
	global_load_lds_dwordx4 v[148:149], off
	v_lshl_add_u64 v[148:149], s[42:43], 0, v[130:131]
	s_mov_b32 m0, s77
	s_nop 0
	global_load_lds_dwordx4 v[148:149], off
	v_lshl_add_u64 v[148:149], v[168:169], 0, s[30:31]
	s_mov_b32 m0, s74
	s_nop 0
	global_load_lds_dwordx4 v[148:149], off
	v_lshl_add_u64 v[148:149], v[170:171], 0, s[30:31]
	s_mov_b32 m0, s75
	s_nop 0
	global_load_lds_dwordx4 v[148:149], off
	s_waitcnt vmcnt(8)
	s_waitcnt lgkmcnt(0)
	s_barrier
	s_setprio 1
	s_waitcnt lgkmcnt(0)
	v_mfma_f32_16x16x32_bf16 v[62:65], v[144:147], v[200:203], v[62:65]
	v_mfma_f32_16x16x32_bf16 v[58:61], v[154:157], v[200:203], v[58:61]
	v_mfma_f32_16x16x32_bf16 v[54:57], v[144:147], v[208:211], v[54:57]
	v_mfma_f32_16x16x32_bf16 v[50:53], v[154:157], v[208:211], v[50:53]
	v_mfma_f32_16x16x32_bf16 v[38:41], v[144:147], v[216:219], v[38:41]
	v_mfma_f32_16x16x32_bf16 v[34:37], v[154:157], v[216:219], v[34:37]
	v_mfma_f32_16x16x32_bf16 v[22:25], v[144:147], v[224:227], v[22:25]
	v_mfma_f32_16x16x32_bf16 v[18:21], v[154:157], v[224:227], v[18:21]
	v_mfma_f32_16x16x32_bf16 v[62:65], v[150:153], v[204:207], v[62:65]
	v_mfma_f32_16x16x32_bf16 v[58:61], v[158:161], v[204:207], v[58:61]
	v_mfma_f32_16x16x32_bf16 v[54:57], v[150:153], v[212:215], v[54:57]
	v_mfma_f32_16x16x32_bf16 v[50:53], v[158:161], v[212:215], v[50:53]
	v_mfma_f32_16x16x32_bf16 v[38:41], v[150:153], v[220:223], v[38:41]
	v_mfma_f32_16x16x32_bf16 v[34:37], v[158:161], v[220:223], v[34:37]
	v_mfma_f32_16x16x32_bf16 v[22:25], v[150:153], v[228:231], v[22:25]
	v_mfma_f32_16x16x32_bf16 v[18:21], v[158:161], v[228:231], v[18:21]
	s_setprio 0
	s_setprio 1
	v_mfma_f32_16x16x32_bf16 v[46:49], v[162:165], v[200:203], v[46:49]
	v_mfma_f32_16x16x32_bf16 v[42:45], v[192:195], v[200:203], v[42:45]
	v_mfma_f32_16x16x32_bf16 v[30:33], v[162:165], v[208:211], v[30:33]
	v_mfma_f32_16x16x32_bf16 v[26:29], v[192:195], v[208:211], v[26:29]
	v_mfma_f32_16x16x32_bf16 v[14:17], v[162:165], v[216:219], v[14:17]
	s_add_i32 s3, s3, 2
	v_mfma_f32_16x16x32_bf16 v[10:13], v[192:195], v[216:219], v[10:13]
	v_mfma_f32_16x16x32_bf16 v[6:9], v[162:165], v[224:227], v[6:9]
	s_add_u32 s40, s40, 0x100
	v_mfma_f32_16x16x32_bf16 v[2:5], v[192:195], v[224:227], v[2:5]
	v_mfma_f32_16x16x32_bf16 v[46:49], v[188:191], v[204:207], v[46:49]
	s_addc_u32 s41, s41, 0
	v_mfma_f32_16x16x32_bf16 v[42:45], v[196:199], v[204:207], v[42:45]
	v_mfma_f32_16x16x32_bf16 v[30:33], v[188:191], v[212:215], v[30:33]
	s_add_u32 s94, s94, 0x100
	v_mfma_f32_16x16x32_bf16 v[26:29], v[196:199], v[212:215], v[26:29]
	v_mfma_f32_16x16x32_bf16 v[14:17], v[188:191], v[220:223], v[14:17]
	s_addc_u32 s33, s33, 0
	v_mfma_f32_16x16x32_bf16 v[10:13], v[196:199], v[220:223], v[10:13]
	v_mfma_f32_16x16x32_bf16 v[6:9], v[188:191], v[228:231], v[6:9]
	s_cmp_gt_u32 s3, 13
	v_mfma_f32_16x16x32_bf16 v[2:5], v[196:199], v[228:231], v[2:5]
	s_setprio 0
	s_barrier
	s_cbranch_scc0 .LBB0_803
	s_and_b64 vcc, exec, s[6:7]
	s_cbranch_vccz .LBB0_806
	s_barrier
